# trim33 + redundant post-barrier lgkmcnt(0) removed in GEMM compute segments + adjacent vmcnt/lgkmcnt waits merged into one s_waitcnt
# speedup vs baseline: 1.0014x; 1.0014x over previous
.LBB0_160:
	s_andn2_saveexec_b64 s[8:9], s[8:9]
	s_cbranch_execz .LBB0_180
	s_mov_b64 s[8:9], exec
	buffer_wbl2 sc1
	s_waitcnt vmcnt(0) lgkmcnt(0)
	v_mbcnt_lo_u32_b32 v1, s8, 0
	v_mbcnt_hi_u32_b32 v1, s9, v1
	v_cmp_eq_u32_e32 vcc, 0, v1
	s_and_saveexec_b64 s[10:11], vcc
	s_cbranch_execz .LBB0_163
	s_bcnt1_i32_b64 s8, s[8:9]
	v_mov_b32_e32 v2, 0x7000
	v_mov_b32_e32 v3, s8
	global_atomic_add v2, v2, v3, s[4:5] offset:1024 sc0

.LBB0_198:
	s_add_u32 s24, s22, 0x100
	s_addc_u32 s25, s23, 0
	s_and_b64 s[66:67], s[26:27], exec
	s_cselect_b32 s35, 0, s25
	s_cselect_b32 s66, 0, s24
	s_add_u32 s67, s63, s22
	s_addc_u32 s68, s64, s23
	s_and_b64 s[26:27], s[26:27], exec
	s_cselect_b32 s27, s14, s68
	s_cselect_b32 s26, s15, s67
	s_add_i32 s67, 0, 0x10000
	s_add_i32 s68, 0, 0x14000
	v_add_u32_e32 v18, s67, v195
	v_add_u32_e32 v30, s68, v195
	ds_read_b128 v[6:9], v18
	ds_read_b128 v[10:13], v18 offset:1024
	ds_read_b128 v[14:17], v18 offset:2048
	ds_read_b128 v[18:21], v18 offset:3072
	ds_read_b128 v[22:25], v30
	ds_read_b128 v[26:29], v30 offset:1024
	ds_read_b128 v[160:163], v30 offset:2048
	ds_read_b128 v[164:167], v30 offset:3072
	s_add_i32 m0, s48, 0xc000
	s_add_u32 s22, s16, s22
	s_addc_u32 s23, s17, s23
	ds_read_b128 v[168:171], v199
	ds_read_b128 v[172:175], v199 offset:1024
	ds_read_b128 v[186:189], v199 offset:2048
	ds_read_b128 v[200:203], v199 offset:3072
	ds_read_b128 v[204:207], v199 offset:4096
	ds_read_b128 v[208:211], v199 offset:5120
	ds_read_b128 v[214:217], v199 offset:6144
	ds_read_b128 v[218:221], v199 offset:7168
	global_load_lds_dwordx4 v5, s[22:23]
	s_add_i32 m0, s48, 0xe000
	s_nop 0
	global_load_lds_dwordx4 v4, s[22:23]
	s_waitcnt vmcnt(8) lgkmcnt(0)
	s_barrier
	s_setprio 1
	v_mfma_f32_16x16x32_bf16 v[156:159], v[6:9], v[168:171], v[156:159]
	v_mfma_f32_16x16x32_bf16 v[152:155], v[14:17], v[168:171], v[152:155]
	v_mfma_f32_16x16x32_bf16 v[140:143], v[6:9], v[186:189], v[140:143]
	v_mfma_f32_16x16x32_bf16 v[136:139], v[14:17], v[186:189], v[136:139]
	v_mfma_f32_16x16x32_bf16 v[124:127], v[6:9], v[204:207], v[124:127]
	v_mfma_f32_16x16x32_bf16 v[120:123], v[14:17], v[204:207], v[120:123]
	v_mfma_f32_16x16x32_bf16 v[108:111], v[6:9], v[214:217], v[108:111]
	v_mfma_f32_16x16x32_bf16 v[104:107], v[14:17], v[214:217], v[104:107]
	v_mfma_f32_16x16x32_bf16 v[156:159], v[10:13], v[172:175], v[156:159]
	v_mfma_f32_16x16x32_bf16 v[152:155], v[18:21], v[172:175], v[152:155]
	v_mfma_f32_16x16x32_bf16 v[140:143], v[10:13], v[200:203], v[140:143]
	v_mfma_f32_16x16x32_bf16 v[136:139], v[18:21], v[200:203], v[136:139]
	v_mfma_f32_16x16x32_bf16 v[124:127], v[10:13], v[208:211], v[124:127]
	v_mfma_f32_16x16x32_bf16 v[120:123], v[18:21], v[208:211], v[120:123]
	v_mfma_f32_16x16x32_bf16 v[108:111], v[10:13], v[218:221], v[108:111]
	v_mfma_f32_16x16x32_bf16 v[104:107], v[18:21], v[218:221], v[104:107]
	s_setprio 0
	s_setprio 1
	v_mfma_f32_16x16x32_bf16 v[148:151], v[22:25], v[168:171], v[148:151]
	v_mfma_f32_16x16x32_bf16 v[144:147], v[160:163], v[168:171], v[144:147]
	v_mfma_f32_16x16x32_bf16 v[132:135], v[22:25], v[186:189], v[132:135]
	v_mfma_f32_16x16x32_bf16 v[128:131], v[160:163], v[186:189], v[128:131]
	v_mfma_f32_16x16x32_bf16 v[116:119], v[22:25], v[204:207], v[116:119]
	v_mfma_f32_16x16x32_bf16 v[112:115], v[160:163], v[204:207], v[112:115]
	v_mfma_f32_16x16x32_bf16 v[100:103], v[22:25], v[214:217], v[100:103]
	v_mfma_f32_16x16x32_bf16 v[96:99], v[160:163], v[214:217], v[96:99]
	v_mfma_f32_16x16x32_bf16 v[148:151], v[26:29], v[172:175], v[148:151]
	v_mfma_f32_16x16x32_bf16 v[144:147], v[164:167], v[172:175], v[144:147]
	v_mfma_f32_16x16x32_bf16 v[132:135], v[26:29], v[200:203], v[132:135]
	v_mfma_f32_16x16x32_bf16 v[128:131], v[164:167], v[200:203], v[128:131]
	v_mfma_f32_16x16x32_bf16 v[116:119], v[26:29], v[208:211], v[116:119]
	v_mfma_f32_16x16x32_bf16 v[112:115], v[164:167], v[208:211], v[112:115]
	v_mfma_f32_16x16x32_bf16 v[100:103], v[26:29], v[218:221], v[100:103]
	v_mfma_f32_16x16x32_bf16 v[96:99], v[164:167], v[218:221], v[96:99]
	s_setprio 0
	s_barrier
	s_add_i32 s22, s67, s41
	v_lshl_add_u64 v[190:191], s[26:27], 0, v[176:177]
	s_mov_b32 m0, s22
	ds_read_b128 v[168:171], v199 offset:16384
	ds_read_b128 v[172:175], v199 offset:17408
	ds_read_b128 v[186:189], v199 offset:18432
	ds_read_b128 v[200:203], v199 offset:19456
	ds_read_b128 v[204:207], v199 offset:20480
	ds_read_b128 v[208:211], v199 offset:21504
	ds_read_b128 v[214:217], v199 offset:22528
	ds_read_b128 v[218:221], v199 offset:23552
	global_load_lds_dwordx4 v[190:191], off
	s_add_i32 m0, s22, 0x2000
	s_add_u32 s22, s26, 0x40000
	v_lshl_add_u64 v[226:227], s[26:27], 0, v[178:179]
	s_addc_u32 s23, s27, 0
	s_add_i32 s67, s68, s41
	global_load_lds_dwordx4 v[226:227], off
	v_lshl_add_u64 v[4:5], s[22:23], 0, v[176:177]
	s_mov_b32 m0, s67
	v_mov_b32_e32 v181, v213
	global_load_lds_dwordx4 v[4:5], off
	s_add_i32 m0, s67, 0x2000
	v_lshl_add_u64 v[4:5], s[22:23], 0, v[178:179]
	s_add_u32 s22, s10, s66
	global_load_lds_dwordx4 v[4:5], off
	s_addc_u32 s23, s11, s35
	s_mov_b32 m0, s48
	v_lshl_add_u64 v[228:229], s[22:23], 0, v[212:213]
	global_load_lds_dwordx4 v212, s[22:23]
	s_mov_b32 m0, s50
	v_lshl_add_u64 v[230:231], s[22:23], 0, v[180:181]
	global_load_lds_dwordx4 v180, s[22:23]
	s_waitcnt vmcnt(8) lgkmcnt(0)
	s_barrier
	s_setprio 1
	v_mfma_f32_16x16x32_bf16 v[92:95], v[6:9], v[168:171], v[92:95]
	v_mfma_f32_16x16x32_bf16 v[88:91], v[14:17], v[168:171], v[88:91]
	v_mfma_f32_16x16x32_bf16 v[76:79], v[6:9], v[186:189], v[76:79]
	v_mfma_f32_16x16x32_bf16 v[72:75], v[14:17], v[186:189], v[72:75]
	v_mfma_f32_16x16x32_bf16 v[60:63], v[6:9], v[204:207], v[60:63]
	v_mfma_f32_16x16x32_bf16 v[56:59], v[14:17], v[204:207], v[56:59]
	v_mfma_f32_16x16x32_bf16 v[4:7], v[6:9], v[214:217], v[44:47]
	v_mfma_f32_16x16x32_bf16 v[92:95], v[10:13], v[172:175], v[92:95]
	v_mfma_f32_16x16x32_bf16 v[88:91], v[18:21], v[172:175], v[88:91]
	v_mfma_f32_16x16x32_bf16 v[76:79], v[10:13], v[200:203], v[76:79]
	v_mfma_f32_16x16x32_bf16 v[72:75], v[18:21], v[200:203], v[72:75]
	v_mfma_f32_16x16x32_bf16 v[60:63], v[10:13], v[208:211], v[60:63]
	v_mfma_f32_16x16x32_bf16 v[56:59], v[18:21], v[208:211], v[56:59]
	v_mfma_f32_16x16x32_bf16 v[4:7], v[10:13], v[218:221], v[4:7]
	v_mfma_f32_16x16x32_bf16 v[8:11], v[14:17], v[214:217], v[40:43]
	v_mfma_f32_16x16x32_bf16 v[8:11], v[18:21], v[218:221], v[8:11]
	s_setprio 0
	s_setprio 1
	v_mfma_f32_16x16x32_bf16 v[40:43], v[22:25], v[186:189], v[68:71]
	v_mfma_f32_16x16x32_bf16 v[68:71], v[26:29], v[200:203], v[40:43]
	v_mfma_f32_16x16x32_bf16 v[40:43], v[160:163], v[186:189], v[64:67]
	v_mfma_f32_16x16x32_bf16 v[64:67], v[164:167], v[200:203], v[40:43]
	v_mfma_f32_16x16x32_bf16 v[40:43], v[22:25], v[204:207], v[52:55]
	v_mfma_f32_16x16x32_bf16 v[12:15], v[22:25], v[168:171], v[84:87]
	v_mfma_f32_16x16x32_bf16 v[52:55], v[26:29], v[208:211], v[40:43]
	v_mfma_f32_16x16x32_bf16 v[40:43], v[160:163], v[204:207], v[48:51]
	v_mfma_f32_16x16x32_bf16 v[20:23], v[22:25], v[214:217], v[36:39]
	v_mfma_f32_16x16x32_bf16 v[12:15], v[26:29], v[172:175], v[12:15]
	v_mfma_f32_16x16x32_bf16 v[16:19], v[160:163], v[168:171], v[80:83]
	v_mfma_f32_16x16x32_bf16 v[48:51], v[164:167], v[208:211], v[40:43]
	v_mfma_f32_16x16x32_bf16 v[20:23], v[26:29], v[218:221], v[20:23]
	v_mfma_f32_16x16x32_bf16 v[24:27], v[160:163], v[214:217], v[32:35]
	v_mfma_f32_16x16x32_bf16 v[16:19], v[164:167], v[172:175], v[16:19]
	v_mfma_f32_16x16x32_bf16 v[24:27], v[164:167], v[218:221], v[24:27]
	s_setprio 0
	s_barrier
	s_add_i32 s35, 0, 0x18000
	s_add_i32 s66, 0, 0x1c000
	v_add_u32_e32 v40, s35, v195
	v_add_u32_e32 v44, s66, v195
	ds_read_b128 v[28:31], v40
	ds_read_b128 v[32:35], v40 offset:1024
	ds_read_b128 v[36:39], v40 offset:2048
	ds_read_b128 v[40:43], v40 offset:3072
	ds_read_b128 v[160:163], v44
	ds_read_b128 v[164:167], v44 offset:1024
	ds_read_b128 v[168:171], v44 offset:2048
	ds_read_b128 v[172:175], v44 offset:3072
	s_mov_b32 m0, s51
	ds_read_b128 v[44:47], v199 offset:32768
	ds_read_b128 v[80:83], v199 offset:33792
	ds_read_b128 v[84:87], v199 offset:34816
	ds_read_b128 v[186:189], v199 offset:35840
	ds_read_b128 v[200:203], v199 offset:36864
	ds_read_b128 v[204:207], v199 offset:37888
	ds_read_b128 v[208:211], v199 offset:38912
	ds_read_b128 v[214:217], v199 offset:39936
	global_load_lds_dwordx4 v192, s[22:23]
	s_mov_b32 m0, s52
	s_nop 0
	global_load_lds_dwordx4 v193, s[22:23]
	s_waitcnt vmcnt(8) lgkmcnt(0)
	s_barrier
	s_setprio 1
	v_mfma_f32_16x16x32_bf16 v[156:159], v[28:31], v[44:47], v[156:159]
	v_mfma_f32_16x16x32_bf16 v[152:155], v[36:39], v[44:47], v[152:155]
	v_mfma_f32_16x16x32_bf16 v[140:143], v[28:31], v[84:87], v[140:143]
	v_mfma_f32_16x16x32_bf16 v[136:139], v[36:39], v[84:87], v[136:139]
	v_mfma_f32_16x16x32_bf16 v[124:127], v[28:31], v[200:203], v[124:127]
	v_mfma_f32_16x16x32_bf16 v[120:123], v[36:39], v[200:203], v[120:123]
	v_mfma_f32_16x16x32_bf16 v[108:111], v[28:31], v[208:211], v[108:111]
	v_mfma_f32_16x16x32_bf16 v[104:107], v[36:39], v[208:211], v[104:107]
	v_mfma_f32_16x16x32_bf16 v[156:159], v[32:35], v[80:83], v[156:159]
	v_mfma_f32_16x16x32_bf16 v[152:155], v[40:43], v[80:83], v[152:155]
	v_mfma_f32_16x16x32_bf16 v[140:143], v[32:35], v[186:189], v[140:143]
	v_mfma_f32_16x16x32_bf16 v[136:139], v[40:43], v[186:189], v[136:139]
	v_mfma_f32_16x16x32_bf16 v[124:127], v[32:35], v[204:207], v[124:127]
	v_mfma_f32_16x16x32_bf16 v[120:123], v[40:43], v[204:207], v[120:123]
	v_mfma_f32_16x16x32_bf16 v[108:111], v[32:35], v[214:217], v[108:111]
	v_mfma_f32_16x16x32_bf16 v[104:107], v[40:43], v[214:217], v[104:107]
	s_setprio 0
	s_setprio 1
	v_mfma_f32_16x16x32_bf16 v[148:151], v[160:163], v[44:47], v[148:151]
	v_mfma_f32_16x16x32_bf16 v[44:47], v[168:171], v[44:47], v[144:147]
	v_mfma_f32_16x16x32_bf16 v[144:147], v[172:175], v[80:83], v[44:47]
	v_mfma_f32_16x16x32_bf16 v[44:47], v[160:163], v[84:87], v[132:135]
	v_mfma_f32_16x16x32_bf16 v[132:135], v[164:167], v[186:189], v[44:47]
	v_mfma_f32_16x16x32_bf16 v[44:47], v[168:171], v[84:87], v[128:131]
	v_mfma_f32_16x16x32_bf16 v[128:131], v[172:175], v[186:189], v[44:47]
	v_mfma_f32_16x16x32_bf16 v[44:47], v[160:163], v[200:203], v[116:119]
	v_mfma_f32_16x16x32_bf16 v[116:119], v[164:167], v[204:207], v[44:47]
	v_mfma_f32_16x16x32_bf16 v[44:47], v[168:171], v[200:203], v[112:115]
	v_mfma_f32_16x16x32_bf16 v[112:115], v[172:175], v[204:207], v[44:47]
	v_mfma_f32_16x16x32_bf16 v[44:47], v[160:163], v[208:211], v[100:103]
	v_mfma_f32_16x16x32_bf16 v[100:103], v[164:167], v[214:217], v[44:47]
	v_mfma_f32_16x16x32_bf16 v[44:47], v[168:171], v[208:211], v[96:99]
	v_mfma_f32_16x16x32_bf16 v[148:151], v[164:167], v[80:83], v[148:151]
	v_mfma_f32_16x16x32_bf16 v[96:99], v[172:175], v[214:217], v[44:47]
	s_setprio 0
	s_barrier
	s_add_i32 s22, s35, s41
	s_nop 2
	v_lshl_add_u64 v[44:45], v[190:191], 0, s[44:45]
	s_mov_b32 m0, s22
	ds_read_b128 v[80:83], v199 offset:49152
	ds_read_b128 v[186:189], v199 offset:50176
	ds_read_b128 v[200:203], v199 offset:51200
	ds_read_b128 v[204:207], v199 offset:52224
	ds_read_b128 v[208:211], v199 offset:53248
	ds_read_b128 v[214:217], v199 offset:54272
	ds_read_b128 v[218:221], v199 offset:55296
	ds_read_b128 v[222:225], v199 offset:56320
	global_load_lds_dwordx4 v[44:45], off
	s_add_i32 m0, s22, 0x2000
	s_add_u32 s22, s26, 0x40080
	v_lshl_add_u64 v[44:45], v[226:227], 0, s[44:45]
	s_addc_u32 s23, s27, 0
	s_add_i32 s26, s66, s41
	global_load_lds_dwordx4 v[44:45], off
	v_lshl_add_u64 v[44:45], s[22:23], 0, v[176:177]
	s_mov_b32 m0, s26
	s_nop 0
	global_load_lds_dwordx4 v[44:45], off
	v_lshl_add_u64 v[44:45], s[22:23], 0, v[178:179]
	s_add_i32 m0, s26, 0x2000
	s_nop 0
	global_load_lds_dwordx4 v[44:45], off
	v_lshl_add_u64 v[44:45], v[228:229], 0, s[44:45]
	s_mov_b32 m0, s54
	s_nop 0
	global_load_lds_dwordx4 v[44:45], off
	v_lshl_add_u64 v[44:45], v[230:231], 0, s[44:45]
	s_mov_b32 m0, s55
	s_nop 0
	global_load_lds_dwordx4 v[44:45], off
	s_waitcnt vmcnt(8) lgkmcnt(0)
	s_barrier
	s_setprio 1
	v_mfma_f32_16x16x32_bf16 v[44:47], v[28:31], v[80:83], v[92:95]
	v_mfma_f32_16x16x32_bf16 v[92:95], v[32:35], v[186:189], v[44:47]
	v_mfma_f32_16x16x32_bf16 v[44:47], v[36:39], v[80:83], v[88:91]
	v_mfma_f32_16x16x32_bf16 v[88:91], v[40:43], v[186:189], v[44:47]
	v_mfma_f32_16x16x32_bf16 v[44:47], v[28:31], v[200:203], v[76:79]
	v_mfma_f32_16x16x32_bf16 v[76:79], v[32:35], v[204:207], v[44:47]
	v_mfma_f32_16x16x32_bf16 v[44:47], v[36:39], v[200:203], v[72:75]
	v_mfma_f32_16x16x32_bf16 v[72:75], v[40:43], v[204:207], v[44:47]
	v_mfma_f32_16x16x32_bf16 v[44:47], v[28:31], v[208:211], v[60:63]
	v_mfma_f32_16x16x32_bf16 v[60:63], v[32:35], v[214:217], v[44:47]
	v_mfma_f32_16x16x32_bf16 v[44:47], v[36:39], v[208:211], v[56:59]
	v_mfma_f32_16x16x32_bf16 v[4:7], v[28:31], v[218:221], v[4:7]
	v_mfma_f32_16x16x32_bf16 v[56:59], v[40:43], v[214:217], v[44:47]
	v_mfma_f32_16x16x32_bf16 v[44:47], v[32:35], v[222:225], v[4:7]
	v_mfma_f32_16x16x32_bf16 v[4:7], v[36:39], v[218:221], v[8:11]
	v_mfma_f32_16x16x32_bf16 v[40:43], v[40:43], v[222:225], v[4:7]
	s_setprio 0
	s_setprio 1
	v_mfma_f32_16x16x32_bf16 v[4:7], v[160:163], v[80:83], v[12:15]
	v_mfma_f32_16x16x32_bf16 v[84:87], v[164:167], v[186:189], v[4:7]
	v_mfma_f32_16x16x32_bf16 v[4:7], v[168:171], v[80:83], v[16:19]
	v_mfma_f32_16x16x32_bf16 v[80:83], v[172:175], v[186:189], v[4:7]
	v_mfma_f32_16x16x32_bf16 v[4:7], v[160:163], v[200:203], v[68:71]
	v_mfma_f32_16x16x32_bf16 v[68:71], v[164:167], v[204:207], v[4:7]
	v_mfma_f32_16x16x32_bf16 v[4:7], v[168:171], v[200:203], v[64:67]
	v_mfma_f32_16x16x32_bf16 v[64:67], v[172:175], v[204:207], v[4:7]
	v_mfma_f32_16x16x32_bf16 v[4:7], v[160:163], v[208:211], v[52:55]
	v_mfma_f32_16x16x32_bf16 v[52:55], v[164:167], v[214:217], v[4:7]
	v_mfma_f32_16x16x32_bf16 v[4:7], v[168:171], v[208:211], v[48:51]
	v_mfma_f32_16x16x32_bf16 v[48:51], v[172:175], v[214:217], v[4:7]
	v_mfma_f32_16x16x32_bf16 v[4:7], v[160:163], v[218:221], v[20:23]
	v_mfma_f32_16x16x32_bf16 v[36:39], v[164:167], v[222:225], v[4:7]
	v_mfma_f32_16x16x32_bf16 v[4:7], v[168:171], v[218:221], v[24:27]
	v_mfma_f32_16x16x32_bf16 v[32:35], v[172:175], v[222:225], v[4:7]
	s_setprio 0
	s_barrier
	s_add_i32 s65, s65, 2
	s_cmp_gt_u32 s65, 13
	s_cbranch_scc1 .LBB0_200
	s_mov_b64 s[22:23], s[24:25]
	s_nop 0
	v_mov_b32_e32 v4, v193
	v_mov_b32_e32 v5, v192
	s_branch .LBB0_196

.LBB0_235:
	s_add_u32 s24, s22, 0x100
	s_addc_u32 s25, s23, 0
	s_and_b64 s[56:57], s[26:27], exec
	s_cselect_b32 s35, 0, s25
	s_cselect_b32 s56, 0, s24
	s_add_u32 s57, s31, s22
	s_addc_u32 s58, s54, s23
	s_and_b64 s[26:27], s[26:27], exec
	s_cselect_b32 s27, s14, s58
	s_cselect_b32 s26, s15, s57
	s_add_i32 s57, 0, 0x10000
	s_add_i32 s58, 0, 0x14000
	v_add_u32_e32 v146, s57, v170
	v_add_u32_e32 v150, s58, v170
	ds_read_b128 v[134:137], v146
	ds_read_b128 v[138:141], v146 offset:1024
	ds_read_b128 v[142:145], v146 offset:2048
	ds_read_b128 v[146:149], v146 offset:3072
	ds_read_b128 v[176:179], v150
	ds_read_b128 v[180:183], v150 offset:1024
	ds_read_b128 v[184:187], v150 offset:2048
	ds_read_b128 v[188:191], v150 offset:3072
	s_add_i32 m0, s36, 0xc000
	s_add_u32 s22, s16, s22
	s_addc_u32 s23, s17, s23
	ds_read_b128 v[192:195], v174
	ds_read_b128 v[196:199], v174 offset:1024
	ds_read_b128 v[200:203], v174 offset:2048
	ds_read_b128 v[204:207], v174 offset:3072
	ds_read_b128 v[208:211], v174 offset:4096
	ds_read_b128 v[214:217], v174 offset:5120
	ds_read_b128 v[218:221], v174 offset:6144
	ds_read_b128 v[222:225], v174 offset:7168
	global_load_lds_dwordx4 v133, s[22:23]
	s_add_i32 m0, s36, 0xe000
	s_nop 0
	global_load_lds_dwordx4 v132, s[22:23]
	s_waitcnt vmcnt(8) lgkmcnt(0)
	s_barrier
	s_setprio 1
	v_mfma_f32_16x16x32_bf16 v[124:127], v[134:137], v[192:195], v[124:127]
	v_mfma_f32_16x16x32_bf16 v[120:123], v[142:145], v[192:195], v[120:123]
	v_mfma_f32_16x16x32_bf16 v[108:111], v[134:137], v[200:203], v[108:111]
	v_mfma_f32_16x16x32_bf16 v[104:107], v[142:145], v[200:203], v[104:107]
	v_mfma_f32_16x16x32_bf16 v[92:95], v[134:137], v[208:211], v[92:95]
	v_mfma_f32_16x16x32_bf16 v[88:91], v[142:145], v[208:211], v[88:91]
	v_mfma_f32_16x16x32_bf16 v[76:79], v[134:137], v[218:221], v[76:79]
	v_mfma_f32_16x16x32_bf16 v[72:75], v[142:145], v[218:221], v[72:75]
	v_mfma_f32_16x16x32_bf16 v[124:127], v[138:141], v[196:199], v[124:127]
	v_mfma_f32_16x16x32_bf16 v[120:123], v[146:149], v[196:199], v[120:123]
	v_mfma_f32_16x16x32_bf16 v[108:111], v[138:141], v[204:207], v[108:111]
	v_mfma_f32_16x16x32_bf16 v[104:107], v[146:149], v[204:207], v[104:107]
	v_mfma_f32_16x16x32_bf16 v[92:95], v[138:141], v[214:217], v[92:95]
	v_mfma_f32_16x16x32_bf16 v[88:91], v[146:149], v[214:217], v[88:91]
	v_mfma_f32_16x16x32_bf16 v[76:79], v[138:141], v[222:225], v[76:79]
	v_mfma_f32_16x16x32_bf16 v[72:75], v[146:149], v[222:225], v[72:75]
	s_setprio 0
	s_setprio 1
	v_mfma_f32_16x16x32_bf16 v[116:119], v[176:179], v[192:195], v[116:119]
	v_mfma_f32_16x16x32_bf16 v[112:115], v[184:187], v[192:195], v[112:115]
	v_mfma_f32_16x16x32_bf16 v[100:103], v[176:179], v[200:203], v[100:103]
	v_mfma_f32_16x16x32_bf16 v[96:99], v[184:187], v[200:203], v[96:99]
	v_mfma_f32_16x16x32_bf16 v[84:87], v[176:179], v[208:211], v[84:87]
	v_mfma_f32_16x16x32_bf16 v[80:83], v[184:187], v[208:211], v[80:83]
	v_mfma_f32_16x16x32_bf16 v[68:71], v[176:179], v[218:221], v[68:71]
	v_mfma_f32_16x16x32_bf16 v[64:67], v[184:187], v[218:221], v[64:67]
	v_mfma_f32_16x16x32_bf16 v[116:119], v[180:183], v[196:199], v[116:119]
	v_mfma_f32_16x16x32_bf16 v[112:115], v[188:191], v[196:199], v[112:115]
	v_mfma_f32_16x16x32_bf16 v[100:103], v[180:183], v[204:207], v[100:103]
	v_mfma_f32_16x16x32_bf16 v[96:99], v[188:191], v[204:207], v[96:99]
	v_mfma_f32_16x16x32_bf16 v[84:87], v[180:183], v[214:217], v[84:87]
	v_mfma_f32_16x16x32_bf16 v[80:83], v[188:191], v[214:217], v[80:83]
	v_mfma_f32_16x16x32_bf16 v[68:71], v[180:183], v[222:225], v[68:71]
	v_mfma_f32_16x16x32_bf16 v[64:67], v[188:191], v[222:225], v[64:67]
	s_setprio 0
	s_barrier
	s_add_i32 s22, s57, s34
	v_lshl_add_u64 v[162:163], s[26:27], 0, v[154:155]
	s_mov_b32 m0, s22
	ds_read_b128 v[192:195], v174 offset:16384
	ds_read_b128 v[196:199], v174 offset:17408
	ds_read_b128 v[200:203], v174 offset:18432
	ds_read_b128 v[204:207], v174 offset:19456
	ds_read_b128 v[208:211], v174 offset:20480
	ds_read_b128 v[214:217], v174 offset:21504
	ds_read_b128 v[218:221], v174 offset:22528
	ds_read_b128 v[222:225], v174 offset:23552
	global_load_lds_dwordx4 v[162:163], off
	s_add_i32 m0, s22, 0x2000
	s_add_u32 s22, s26, 0x40000
	v_lshl_add_u64 v[166:167], s[26:27], 0, v[152:153]
	s_addc_u32 s23, s27, 0
	s_add_i32 s57, s58, s34
	global_load_lds_dwordx4 v[166:167], off
	v_lshl_add_u64 v[132:133], s[22:23], 0, v[154:155]
	s_mov_b32 m0, s57
	v_mov_b32_e32 v157, v213
	global_load_lds_dwordx4 v[132:133], off
	s_add_i32 m0, s57, 0x2000
	v_lshl_add_u64 v[132:133], s[22:23], 0, v[152:153]
	s_add_u32 s22, s10, s56
	global_load_lds_dwordx4 v[132:133], off
	s_addc_u32 s23, s11, s35
	s_mov_b32 m0, s36
	v_lshl_add_u64 v[226:227], s[22:23], 0, v[212:213]
	global_load_lds_dwordx4 v212, s[22:23]
	s_mov_b32 m0, s37
	v_lshl_add_u64 v[228:229], s[22:23], 0, v[156:157]
	global_load_lds_dwordx4 v156, s[22:23]
	s_waitcnt vmcnt(8) lgkmcnt(0)
	s_barrier
	s_setprio 1
	v_mfma_f32_16x16x32_bf16 v[60:63], v[134:137], v[192:195], v[60:63]
	v_mfma_f32_16x16x32_bf16 v[56:59], v[142:145], v[192:195], v[56:59]
	v_mfma_f32_16x16x32_bf16 v[44:47], v[134:137], v[200:203], v[44:47]
	v_mfma_f32_16x16x32_bf16 v[40:43], v[142:145], v[200:203], v[40:43]
	v_mfma_f32_16x16x32_bf16 v[28:31], v[134:137], v[208:211], v[28:31]
	v_mfma_f32_16x16x32_bf16 v[24:27], v[142:145], v[208:211], v[24:27]
	v_mfma_f32_16x16x32_bf16 v[12:15], v[134:137], v[218:221], v[12:15]
	v_mfma_f32_16x16x32_bf16 v[8:11], v[142:145], v[218:221], v[8:11]
	v_mfma_f32_16x16x32_bf16 v[60:63], v[138:141], v[196:199], v[60:63]
	v_mfma_f32_16x16x32_bf16 v[56:59], v[146:149], v[196:199], v[56:59]
	v_mfma_f32_16x16x32_bf16 v[44:47], v[138:141], v[204:207], v[44:47]
	v_mfma_f32_16x16x32_bf16 v[40:43], v[146:149], v[204:207], v[40:43]
	v_mfma_f32_16x16x32_bf16 v[28:31], v[138:141], v[214:217], v[28:31]
	v_mfma_f32_16x16x32_bf16 v[24:27], v[146:149], v[214:217], v[24:27]
	v_mfma_f32_16x16x32_bf16 v[12:15], v[138:141], v[222:225], v[12:15]
	v_mfma_f32_16x16x32_bf16 v[8:11], v[146:149], v[222:225], v[8:11]
	s_setprio 0
	s_setprio 1
	v_mfma_f32_16x16x32_bf16 v[52:55], v[176:179], v[192:195], v[52:55]
	v_mfma_f32_16x16x32_bf16 v[48:51], v[184:187], v[192:195], v[48:51]
	v_mfma_f32_16x16x32_bf16 v[36:39], v[176:179], v[200:203], v[36:39]
	v_mfma_f32_16x16x32_bf16 v[32:35], v[184:187], v[200:203], v[32:35]
	v_mfma_f32_16x16x32_bf16 v[20:23], v[176:179], v[208:211], v[20:23]
	v_mfma_f32_16x16x32_bf16 v[16:19], v[184:187], v[208:211], v[16:19]
	v_mfma_f32_16x16x32_bf16 v[4:7], v[176:179], v[218:221], v[4:7]
	v_mfma_f32_16x16x32_bf16 v[0:3], v[184:187], v[218:221], v[0:3]
	v_mfma_f32_16x16x32_bf16 v[52:55], v[180:183], v[196:199], v[52:55]
	v_mfma_f32_16x16x32_bf16 v[48:51], v[188:191], v[196:199], v[48:51]
	v_mfma_f32_16x16x32_bf16 v[36:39], v[180:183], v[204:207], v[36:39]
	v_mfma_f32_16x16x32_bf16 v[32:35], v[188:191], v[204:207], v[32:35]
	v_mfma_f32_16x16x32_bf16 v[20:23], v[180:183], v[214:217], v[20:23]
	v_mfma_f32_16x16x32_bf16 v[16:19], v[188:191], v[214:217], v[16:19]
	v_mfma_f32_16x16x32_bf16 v[4:7], v[180:183], v[222:225], v[4:7]
	v_mfma_f32_16x16x32_bf16 v[0:3], v[188:191], v[222:225], v[0:3]
	s_setprio 0
	s_barrier
	s_add_i32 s35, 0, 0x18000
	s_add_i32 s56, 0, 0x1c000
	v_add_u32_e32 v144, s35, v170
	v_add_u32_e32 v157, s56, v170
	ds_read_b128 v[132:135], v144
	ds_read_b128 v[136:139], v144 offset:1024
	ds_read_b128 v[140:143], v144 offset:2048
	ds_read_b128 v[144:147], v144 offset:3072
	ds_read_b128 v[148:151], v157
	ds_read_b128 v[176:179], v157 offset:1024
	ds_read_b128 v[180:183], v157 offset:2048
	ds_read_b128 v[184:187], v157 offset:3072
	s_mov_b32 m0, s38
	ds_read_b128 v[188:191], v174 offset:32768
	ds_read_b128 v[192:195], v174 offset:33792
	ds_read_b128 v[196:199], v174 offset:34816
	ds_read_b128 v[200:203], v174 offset:35840
	ds_read_b128 v[204:207], v174 offset:36864
	ds_read_b128 v[208:211], v174 offset:37888
	ds_read_b128 v[214:217], v174 offset:38912
	ds_read_b128 v[218:221], v174 offset:39936
	global_load_lds_dwordx4 v165, s[22:23]
	s_mov_b32 m0, s40
	s_nop 0
	global_load_lds_dwordx4 v168, s[22:23]
	s_waitcnt vmcnt(8) lgkmcnt(0)
	s_barrier
	s_setprio 1
	v_mfma_f32_16x16x32_bf16 v[124:127], v[132:135], v[188:191], v[124:127]
	v_mfma_f32_16x16x32_bf16 v[120:123], v[140:143], v[188:191], v[120:123]
	v_mfma_f32_16x16x32_bf16 v[108:111], v[132:135], v[196:199], v[108:111]
	v_mfma_f32_16x16x32_bf16 v[104:107], v[140:143], v[196:199], v[104:107]
	v_mfma_f32_16x16x32_bf16 v[92:95], v[132:135], v[204:207], v[92:95]
	v_mfma_f32_16x16x32_bf16 v[88:91], v[140:143], v[204:207], v[88:91]
	v_mfma_f32_16x16x32_bf16 v[76:79], v[132:135], v[214:217], v[76:79]
	v_mfma_f32_16x16x32_bf16 v[72:75], v[140:143], v[214:217], v[72:75]
	v_mfma_f32_16x16x32_bf16 v[124:127], v[136:139], v[192:195], v[124:127]
	v_mfma_f32_16x16x32_bf16 v[120:123], v[144:147], v[192:195], v[120:123]
	v_mfma_f32_16x16x32_bf16 v[108:111], v[136:139], v[200:203], v[108:111]
	v_mfma_f32_16x16x32_bf16 v[104:107], v[144:147], v[200:203], v[104:107]
	v_mfma_f32_16x16x32_bf16 v[92:95], v[136:139], v[208:211], v[92:95]
	v_mfma_f32_16x16x32_bf16 v[88:91], v[144:147], v[208:211], v[88:91]
	v_mfma_f32_16x16x32_bf16 v[76:79], v[136:139], v[218:221], v[76:79]
	v_mfma_f32_16x16x32_bf16 v[72:75], v[144:147], v[218:221], v[72:75]
	s_setprio 0
	s_setprio 1
	v_mfma_f32_16x16x32_bf16 v[116:119], v[148:151], v[188:191], v[116:119]
	v_mfma_f32_16x16x32_bf16 v[112:115], v[180:183], v[188:191], v[112:115]
	v_mfma_f32_16x16x32_bf16 v[100:103], v[148:151], v[196:199], v[100:103]
	v_mfma_f32_16x16x32_bf16 v[96:99], v[180:183], v[196:199], v[96:99]
	v_mfma_f32_16x16x32_bf16 v[84:87], v[148:151], v[204:207], v[84:87]
	v_mfma_f32_16x16x32_bf16 v[80:83], v[180:183], v[204:207], v[80:83]
	v_mfma_f32_16x16x32_bf16 v[68:71], v[148:151], v[214:217], v[68:71]
	v_mfma_f32_16x16x32_bf16 v[64:67], v[180:183], v[214:217], v[64:67]
	v_mfma_f32_16x16x32_bf16 v[116:119], v[176:179], v[192:195], v[116:119]
	v_mfma_f32_16x16x32_bf16 v[112:115], v[184:187], v[192:195], v[112:115]
	v_mfma_f32_16x16x32_bf16 v[100:103], v[176:179], v[200:203], v[100:103]
	v_mfma_f32_16x16x32_bf16 v[96:99], v[184:187], v[200:203], v[96:99]
	v_mfma_f32_16x16x32_bf16 v[84:87], v[176:179], v[208:211], v[84:87]
	v_mfma_f32_16x16x32_bf16 v[80:83], v[184:187], v[208:211], v[80:83]
	v_mfma_f32_16x16x32_bf16 v[68:71], v[176:179], v[218:221], v[68:71]
	v_mfma_f32_16x16x32_bf16 v[64:67], v[184:187], v[218:221], v[64:67]
	s_setprio 0
	s_barrier
	s_add_i32 s22, s35, s34
	v_lshl_add_u64 v[162:163], v[162:163], 0, s[44:45]
	s_mov_b32 m0, s22
	ds_read_b128 v[188:191], v174 offset:49152
	ds_read_b128 v[192:195], v174 offset:50176
	ds_read_b128 v[196:199], v174 offset:51200
	ds_read_b128 v[200:203], v174 offset:52224
	ds_read_b128 v[204:207], v174 offset:53248
	ds_read_b128 v[208:211], v174 offset:54272
	ds_read_b128 v[214:217], v174 offset:55296
	ds_read_b128 v[218:221], v174 offset:56320
	global_load_lds_dwordx4 v[162:163], off
	s_add_i32 m0, s22, 0x2000
	s_add_u32 s22, s26, 0x40080
	v_lshl_add_u64 v[162:163], v[166:167], 0, s[44:45]
	s_addc_u32 s23, s27, 0
	s_add_i32 s26, s56, s34
	global_load_lds_dwordx4 v[162:163], off
	v_lshl_add_u64 v[162:163], s[22:23], 0, v[154:155]
	s_mov_b32 m0, s26
	s_nop 0
	global_load_lds_dwordx4 v[162:163], off
	v_lshl_add_u64 v[162:163], s[22:23], 0, v[152:153]
	s_add_i32 m0, s26, 0x2000
	s_nop 0
	global_load_lds_dwordx4 v[162:163], off
	v_lshl_add_u64 v[162:163], v[226:227], 0, s[44:45]
	s_mov_b32 m0, s41
	s_nop 0
	global_load_lds_dwordx4 v[162:163], off
	v_lshl_add_u64 v[162:163], v[228:229], 0, s[44:45]
	s_mov_b32 m0, s48
	s_nop 0
	global_load_lds_dwordx4 v[162:163], off
	s_waitcnt vmcnt(8) lgkmcnt(0)
	s_barrier
	s_setprio 1
	v_mfma_f32_16x16x32_bf16 v[60:63], v[132:135], v[188:191], v[60:63]
	v_mfma_f32_16x16x32_bf16 v[56:59], v[140:143], v[188:191], v[56:59]
	v_mfma_f32_16x16x32_bf16 v[44:47], v[132:135], v[196:199], v[44:47]
	v_mfma_f32_16x16x32_bf16 v[40:43], v[140:143], v[196:199], v[40:43]
	v_mfma_f32_16x16x32_bf16 v[28:31], v[132:135], v[204:207], v[28:31]
	v_mfma_f32_16x16x32_bf16 v[24:27], v[140:143], v[204:207], v[24:27]
	v_mfma_f32_16x16x32_bf16 v[12:15], v[132:135], v[214:217], v[12:15]
	v_mfma_f32_16x16x32_bf16 v[8:11], v[140:143], v[214:217], v[8:11]
	v_mfma_f32_16x16x32_bf16 v[60:63], v[136:139], v[192:195], v[60:63]
	v_mfma_f32_16x16x32_bf16 v[56:59], v[144:147], v[192:195], v[56:59]
	v_mfma_f32_16x16x32_bf16 v[44:47], v[136:139], v[200:203], v[44:47]
	v_mfma_f32_16x16x32_bf16 v[40:43], v[144:147], v[200:203], v[40:43]
	v_mfma_f32_16x16x32_bf16 v[28:31], v[136:139], v[208:211], v[28:31]
	v_mfma_f32_16x16x32_bf16 v[24:27], v[144:147], v[208:211], v[24:27]
	v_mfma_f32_16x16x32_bf16 v[12:15], v[136:139], v[218:221], v[12:15]
	v_mfma_f32_16x16x32_bf16 v[8:11], v[144:147], v[218:221], v[8:11]
	s_setprio 0
	s_setprio 1
	v_mfma_f32_16x16x32_bf16 v[52:55], v[148:151], v[188:191], v[52:55]
	v_mfma_f32_16x16x32_bf16 v[48:51], v[180:183], v[188:191], v[48:51]
	v_mfma_f32_16x16x32_bf16 v[36:39], v[148:151], v[196:199], v[36:39]
	v_mfma_f32_16x16x32_bf16 v[32:35], v[180:183], v[196:199], v[32:35]
	v_mfma_f32_16x16x32_bf16 v[20:23], v[148:151], v[204:207], v[20:23]
	v_mfma_f32_16x16x32_bf16 v[16:19], v[180:183], v[204:207], v[16:19]
	v_mfma_f32_16x16x32_bf16 v[4:7], v[148:151], v[214:217], v[4:7]
	v_mfma_f32_16x16x32_bf16 v[0:3], v[180:183], v[214:217], v[0:3]
	v_mfma_f32_16x16x32_bf16 v[52:55], v[176:179], v[192:195], v[52:55]
	v_mfma_f32_16x16x32_bf16 v[48:51], v[184:187], v[192:195], v[48:51]
	v_mfma_f32_16x16x32_bf16 v[36:39], v[176:179], v[200:203], v[36:39]
	v_mfma_f32_16x16x32_bf16 v[32:35], v[184:187], v[200:203], v[32:35]
	v_mfma_f32_16x16x32_bf16 v[20:23], v[176:179], v[208:211], v[20:23]
	v_mfma_f32_16x16x32_bf16 v[16:19], v[184:187], v[208:211], v[16:19]
	v_mfma_f32_16x16x32_bf16 v[4:7], v[176:179], v[218:221], v[4:7]
	v_mfma_f32_16x16x32_bf16 v[0:3], v[184:187], v[218:221], v[0:3]
	s_setprio 0
	s_barrier
	s_add_i32 s55, s55, 2
	s_cmp_gt_u32 s55, 13
	s_cbranch_scc1 .LBB0_237
	s_mov_b64 s[22:23], s[24:25]
	v_mov_b32_e32 v132, v168
	v_mov_b32_e32 v133, v165
	s_branch .LBB0_233

.LBB0_283:
	s_andn2_saveexec_b64 s[12:13], s[12:13]
	s_cbranch_execz .LBB0_303
	s_mov_b64 s[12:13], exec
	buffer_wbl2 sc1
	s_waitcnt vmcnt(0) lgkmcnt(0)
	v_mbcnt_lo_u32_b32 v1, s12, 0
	v_mbcnt_hi_u32_b32 v1, s13, v1
	v_cmp_eq_u32_e32 vcc, 0, v1
	s_and_saveexec_b64 s[14:15], vcc
	s_cbranch_execz .LBB0_286
	s_bcnt1_i32_b64 s12, s[12:13]
	v_mov_b32_e32 v2, s12
	v_mov_b32_e32 v3, 0x7000
	global_atomic_add v2, v3, v2, s[6:7] offset:1024 sc0

.LBB0_534:
	s_andn2_saveexec_b64 s[10:11], s[10:11]
	s_cbranch_execz .LBB0_554
	s_mov_b64 s[10:11], exec
	buffer_wbl2 sc1
	s_waitcnt vmcnt(0) lgkmcnt(0)
	v_mbcnt_lo_u32_b32 v1, s10, 0
	v_mbcnt_hi_u32_b32 v1, s11, v1
	v_cmp_eq_u32_e32 vcc, 0, v1
	s_and_saveexec_b64 s[12:13], vcc
	s_cbranch_execz .LBB0_537
	s_bcnt1_i32_b64 s10, s[10:11]
	v_mov_b32_e32 v2, s10
	v_mov_b32_e32 v3, 0x7000
	global_atomic_add v2, v3, v2, s[6:7] offset:1024 sc0

.LBB0_696:
	s_andn2_saveexec_b64 s[8:9], s[8:9]
	s_cbranch_execz .LBB0_716
	s_mov_b64 s[8:9], exec
	buffer_wbl2 sc1
	s_waitcnt vmcnt(0) lgkmcnt(0)
	v_mbcnt_lo_u32_b32 v1, s8, 0
	v_mbcnt_hi_u32_b32 v1, s9, v1
	v_cmp_eq_u32_e32 vcc, 0, v1
	s_and_saveexec_b64 s[10:11], vcc
	s_cbranch_execz .LBB0_699
	s_bcnt1_i32_b64 s8, s[8:9]
	v_mov_b32_e32 v2, s8
	v_mov_b32_e32 v3, 0x7000
	global_atomic_add v2, v3, v2, s[4:5] offset:1024 sc0

.LBB0_734:
	s_add_i32 s60, s60, 2
	s_add_u32 s24, s22, 0x100
	s_addc_u32 s25, s23, 0
	s_and_b64 s[62:63], s[26:27], exec
	s_cselect_b32 s35, 0, s25
	s_cselect_b32 s61, 0, s24
	s_add_u32 s62, s21, s22
	s_addc_u32 s63, s59, s23
	s_and_b64 s[26:27], s[26:27], exec
	s_cselect_b32 s27, s14, s63
	s_cselect_b32 s26, s15, s62
	s_add_i32 s62, 0, 0x10000
	v_add_u32_e32 v146, s62, v173
	s_add_i32 s63, 0, 0x14000
	ds_read_b128 v[134:137], v146
	ds_read_b128 v[138:141], v146 offset:1024
	ds_read_b128 v[142:145], v146 offset:2048
	ds_read_b128 v[154:157], v146 offset:3072
	v_add_u32_e32 v146, s63, v173
	ds_read_b128 v[158:161], v146
	ds_read_b128 v[162:165], v146 offset:1024
	ds_read_b128 v[176:179], v146 offset:2048
	ds_read_b128 v[180:183], v146 offset:3072
	s_add_i32 m0, s37, 0xc000
	s_add_u32 s22, s52, s22
	s_addc_u32 s23, s53, s23
	ds_read_b128 v[184:187], v175
	ds_read_b128 v[188:191], v175 offset:1024
	ds_read_b128 v[192:195], v175 offset:2048
	ds_read_b128 v[196:199], v175 offset:3072
	ds_read_b128 v[200:203], v175 offset:4096
	ds_read_b128 v[204:207], v175 offset:5120
	ds_read_b128 v[208:211], v175 offset:6144
	ds_read_b128 v[214:217], v175 offset:7168
	global_load_lds_dwordx4 v133, s[22:23]
	s_add_i32 m0, s37, 0xe000
	s_nop 0
	global_load_lds_dwordx4 v132, s[22:23]
	s_waitcnt vmcnt(8) lgkmcnt(0)
	s_barrier
	s_setprio 1
	v_mfma_f32_16x16x32_bf16 v[124:127], v[134:137], v[184:187], v[124:127]
	v_mfma_f32_16x16x32_bf16 v[120:123], v[142:145], v[184:187], v[120:123]
	v_mfma_f32_16x16x32_bf16 v[108:111], v[134:137], v[192:195], v[108:111]
	v_mfma_f32_16x16x32_bf16 v[104:107], v[142:145], v[192:195], v[104:107]
	v_mfma_f32_16x16x32_bf16 v[92:95], v[134:137], v[200:203], v[92:95]
	v_mfma_f32_16x16x32_bf16 v[88:91], v[142:145], v[200:203], v[88:91]
	v_mfma_f32_16x16x32_bf16 v[80:83], v[134:137], v[208:211], v[80:83]
	v_mfma_f32_16x16x32_bf16 v[72:75], v[142:145], v[208:211], v[72:75]
	v_mfma_f32_16x16x32_bf16 v[124:127], v[138:141], v[188:191], v[124:127]
	v_mfma_f32_16x16x32_bf16 v[120:123], v[154:157], v[188:191], v[120:123]
	v_mfma_f32_16x16x32_bf16 v[108:111], v[138:141], v[196:199], v[108:111]
	v_mfma_f32_16x16x32_bf16 v[104:107], v[154:157], v[196:199], v[104:107]
	v_mfma_f32_16x16x32_bf16 v[92:95], v[138:141], v[204:207], v[92:95]
	v_mfma_f32_16x16x32_bf16 v[88:91], v[154:157], v[204:207], v[88:91]
	v_mfma_f32_16x16x32_bf16 v[80:83], v[138:141], v[214:217], v[80:83]
	v_mfma_f32_16x16x32_bf16 v[72:75], v[154:157], v[214:217], v[72:75]
	s_setprio 0
	s_setprio 1
	v_mfma_f32_16x16x32_bf16 v[116:119], v[158:161], v[184:187], v[116:119]
	v_mfma_f32_16x16x32_bf16 v[112:115], v[176:179], v[184:187], v[112:115]
	v_mfma_f32_16x16x32_bf16 v[100:103], v[158:161], v[192:195], v[100:103]
	v_mfma_f32_16x16x32_bf16 v[96:99], v[176:179], v[192:195], v[96:99]
	v_mfma_f32_16x16x32_bf16 v[84:87], v[158:161], v[200:203], v[84:87]
	v_mfma_f32_16x16x32_bf16 v[76:79], v[176:179], v[200:203], v[76:79]
	v_mfma_f32_16x16x32_bf16 v[68:71], v[158:161], v[208:211], v[68:71]
	v_mfma_f32_16x16x32_bf16 v[64:67], v[176:179], v[208:211], v[64:67]
	v_mfma_f32_16x16x32_bf16 v[116:119], v[162:165], v[188:191], v[116:119]
	v_mfma_f32_16x16x32_bf16 v[112:115], v[180:183], v[188:191], v[112:115]
	v_mfma_f32_16x16x32_bf16 v[100:103], v[162:165], v[196:199], v[100:103]
	v_mfma_f32_16x16x32_bf16 v[96:99], v[180:183], v[196:199], v[96:99]
	v_mfma_f32_16x16x32_bf16 v[84:87], v[162:165], v[204:207], v[84:87]
	v_mfma_f32_16x16x32_bf16 v[76:79], v[180:183], v[204:207], v[76:79]
	v_mfma_f32_16x16x32_bf16 v[68:71], v[162:165], v[214:217], v[68:71]
	v_mfma_f32_16x16x32_bf16 v[64:67], v[180:183], v[214:217], v[64:67]
	s_setprio 0
	s_barrier
	s_add_i32 s22, s62, s36
	v_lshl_add_u64 v[218:219], s[26:27], 0, v[150:151]
	s_mov_b32 m0, s22
	ds_read_b128 v[184:187], v175 offset:16384
	ds_read_b128 v[188:191], v175 offset:17408
	ds_read_b128 v[192:195], v175 offset:18432
	ds_read_b128 v[196:199], v175 offset:19456
	ds_read_b128 v[200:203], v175 offset:20480
	ds_read_b128 v[204:207], v175 offset:21504
	ds_read_b128 v[208:211], v175 offset:22528
	ds_read_b128 v[214:217], v175 offset:23552
	global_load_lds_dwordx4 v[218:219], off
	s_add_i32 m0, s22, 0x2000
	s_add_u32 s22, s26, s5
	v_lshl_add_u64 v[220:221], s[26:27], 0, v[148:149]
	s_addc_u32 s23, s27, 0
	s_add_i32 s26, s63, s36
	global_load_lds_dwordx4 v[220:221], off
	v_lshl_add_u64 v[222:223], s[22:23], 0, v[150:151]
	s_mov_b32 m0, s26
	v_lshl_add_u64 v[224:225], s[22:23], 0, v[148:149]
	global_load_lds_dwordx4 v[222:223], off
	s_add_i32 m0, s26, 0x2000
	s_add_u32 s22, s6, s61
	global_load_lds_dwordx4 v[224:225], off
	s_addc_u32 s23, s7, s35
	s_mov_b32 m0, s37
	v_mov_b32_e32 v153, v213
	global_load_lds_dwordx4 v212, s[22:23]
	s_mov_b32 m0, s38
	v_lshl_add_u64 v[226:227], s[22:23], 0, v[212:213]
	global_load_lds_dwordx4 v152, s[22:23]
	s_waitcnt vmcnt(8) lgkmcnt(0)
	v_lshl_add_u64 v[228:229], s[22:23], 0, v[152:153]
	s_barrier
	s_setprio 1
	s_waitcnt lgkmcnt(0)
	v_mfma_f32_16x16x32_bf16 v[60:63], v[134:137], v[184:187], v[60:63]
	v_mfma_f32_16x16x32_bf16 v[56:59], v[142:145], v[184:187], v[56:59]
	v_mfma_f32_16x16x32_bf16 v[48:51], v[134:137], v[192:195], v[48:51]
	v_mfma_f32_16x16x32_bf16 v[40:43], v[142:145], v[192:195], v[40:43]
	v_mfma_f32_16x16x32_bf16 v[32:35], v[134:137], v[200:203], v[32:35]
	v_mfma_f32_16x16x32_bf16 v[24:27], v[142:145], v[200:203], v[24:27]
	v_mfma_f32_16x16x32_bf16 v[16:19], v[134:137], v[208:211], v[16:19]
	v_mfma_f32_16x16x32_bf16 v[8:11], v[142:145], v[208:211], v[8:11]
	v_mfma_f32_16x16x32_bf16 v[60:63], v[138:141], v[188:191], v[60:63]
	v_mfma_f32_16x16x32_bf16 v[56:59], v[154:157], v[188:191], v[56:59]
	v_mfma_f32_16x16x32_bf16 v[48:51], v[138:141], v[196:199], v[48:51]
	v_mfma_f32_16x16x32_bf16 v[40:43], v[154:157], v[196:199], v[40:43]
	v_mfma_f32_16x16x32_bf16 v[32:35], v[138:141], v[204:207], v[32:35]
	v_mfma_f32_16x16x32_bf16 v[24:27], v[154:157], v[204:207], v[24:27]
	v_mfma_f32_16x16x32_bf16 v[16:19], v[138:141], v[214:217], v[16:19]
	v_mfma_f32_16x16x32_bf16 v[8:11], v[154:157], v[214:217], v[8:11]
	s_setprio 0
	s_setprio 1
	v_mfma_f32_16x16x32_bf16 v[52:55], v[158:161], v[184:187], v[52:55]
	v_mfma_f32_16x16x32_bf16 v[44:47], v[176:179], v[184:187], v[44:47]
	v_mfma_f32_16x16x32_bf16 v[36:39], v[158:161], v[192:195], v[36:39]
	v_mfma_f32_16x16x32_bf16 v[28:31], v[176:179], v[192:195], v[28:31]
	v_mfma_f32_16x16x32_bf16 v[20:23], v[158:161], v[200:203], v[20:23]
	v_mfma_f32_16x16x32_bf16 v[12:15], v[176:179], v[200:203], v[12:15]
	v_mfma_f32_16x16x32_bf16 v[4:7], v[158:161], v[208:211], v[4:7]
	v_mfma_f32_16x16x32_bf16 v[0:3], v[176:179], v[208:211], v[0:3]
	v_mfma_f32_16x16x32_bf16 v[52:55], v[162:165], v[188:191], v[52:55]
	v_mfma_f32_16x16x32_bf16 v[44:47], v[180:183], v[188:191], v[44:47]
	v_mfma_f32_16x16x32_bf16 v[36:39], v[162:165], v[196:199], v[36:39]
	v_mfma_f32_16x16x32_bf16 v[28:31], v[180:183], v[196:199], v[28:31]
	v_mfma_f32_16x16x32_bf16 v[20:23], v[162:165], v[204:207], v[20:23]
	v_mfma_f32_16x16x32_bf16 v[12:15], v[180:183], v[204:207], v[12:15]
	v_mfma_f32_16x16x32_bf16 v[4:7], v[162:165], v[214:217], v[4:7]
	v_mfma_f32_16x16x32_bf16 v[0:3], v[180:183], v[214:217], v[0:3]
	s_setprio 0
	s_barrier
	s_add_i32 s26, 0, 0x18000
	s_add_i32 s27, 0, 0x1c000
	v_add_u32_e32 v144, s26, v173
	v_add_u32_e32 v153, s27, v173
	ds_read_b128 v[132:135], v144
	ds_read_b128 v[136:139], v144 offset:1024
	ds_read_b128 v[140:143], v144 offset:2048
	ds_read_b128 v[144:147], v144 offset:3072
	ds_read_b128 v[154:157], v153
	ds_read_b128 v[158:161], v153 offset:1024
	ds_read_b128 v[162:165], v153 offset:2048
	ds_read_b128 v[176:179], v153 offset:3072
	s_mov_b32 m0, s40
	ds_read_b128 v[180:183], v175 offset:32768
	ds_read_b128 v[184:187], v175 offset:33792
	ds_read_b128 v[188:191], v175 offset:34816
	ds_read_b128 v[192:195], v175 offset:35840
	ds_read_b128 v[196:199], v175 offset:36864
	ds_read_b128 v[200:203], v175 offset:37888
	ds_read_b128 v[204:207], v175 offset:38912
	ds_read_b128 v[208:211], v175 offset:39936
	global_load_lds_dwordx4 v170, s[22:23]
	s_mov_b32 m0, s41
	s_nop 0
	global_load_lds_dwordx4 v171, s[22:23]
	s_waitcnt vmcnt(8) lgkmcnt(0)
	s_barrier
	s_setprio 1
	v_mfma_f32_16x16x32_bf16 v[124:127], v[132:135], v[180:183], v[124:127]
	v_mfma_f32_16x16x32_bf16 v[120:123], v[140:143], v[180:183], v[120:123]
	v_mfma_f32_16x16x32_bf16 v[108:111], v[132:135], v[188:191], v[108:111]
	v_mfma_f32_16x16x32_bf16 v[104:107], v[140:143], v[188:191], v[104:107]
	v_mfma_f32_16x16x32_bf16 v[92:95], v[132:135], v[196:199], v[92:95]
	v_mfma_f32_16x16x32_bf16 v[88:91], v[140:143], v[196:199], v[88:91]
	v_mfma_f32_16x16x32_bf16 v[80:83], v[132:135], v[204:207], v[80:83]
	v_mfma_f32_16x16x32_bf16 v[72:75], v[140:143], v[204:207], v[72:75]
	v_mfma_f32_16x16x32_bf16 v[124:127], v[136:139], v[184:187], v[124:127]
	v_mfma_f32_16x16x32_bf16 v[120:123], v[144:147], v[184:187], v[120:123]
	v_mfma_f32_16x16x32_bf16 v[108:111], v[136:139], v[192:195], v[108:111]
	v_mfma_f32_16x16x32_bf16 v[104:107], v[144:147], v[192:195], v[104:107]
	v_mfma_f32_16x16x32_bf16 v[92:95], v[136:139], v[200:203], v[92:95]
	v_mfma_f32_16x16x32_bf16 v[88:91], v[144:147], v[200:203], v[88:91]
	v_mfma_f32_16x16x32_bf16 v[80:83], v[136:139], v[208:211], v[80:83]
	v_mfma_f32_16x16x32_bf16 v[72:75], v[144:147], v[208:211], v[72:75]
	s_setprio 0
	s_setprio 1
	v_mfma_f32_16x16x32_bf16 v[116:119], v[154:157], v[180:183], v[116:119]
	v_mfma_f32_16x16x32_bf16 v[112:115], v[162:165], v[180:183], v[112:115]
	v_mfma_f32_16x16x32_bf16 v[100:103], v[154:157], v[188:191], v[100:103]
	v_mfma_f32_16x16x32_bf16 v[96:99], v[162:165], v[188:191], v[96:99]
	v_mfma_f32_16x16x32_bf16 v[84:87], v[154:157], v[196:199], v[84:87]
	v_mfma_f32_16x16x32_bf16 v[76:79], v[162:165], v[196:199], v[76:79]
	v_mfma_f32_16x16x32_bf16 v[68:71], v[154:157], v[204:207], v[68:71]
	v_mfma_f32_16x16x32_bf16 v[64:67], v[162:165], v[204:207], v[64:67]
	v_mfma_f32_16x16x32_bf16 v[116:119], v[158:161], v[184:187], v[116:119]
	v_mfma_f32_16x16x32_bf16 v[112:115], v[176:179], v[184:187], v[112:115]
	v_mfma_f32_16x16x32_bf16 v[100:103], v[158:161], v[192:195], v[100:103]
	v_mfma_f32_16x16x32_bf16 v[96:99], v[176:179], v[192:195], v[96:99]
	v_mfma_f32_16x16x32_bf16 v[84:87], v[158:161], v[200:203], v[84:87]
	v_mfma_f32_16x16x32_bf16 v[76:79], v[176:179], v[200:203], v[76:79]
	v_mfma_f32_16x16x32_bf16 v[68:71], v[158:161], v[208:211], v[68:71]
	v_mfma_f32_16x16x32_bf16 v[64:67], v[176:179], v[208:211], v[64:67]
	s_setprio 0
	s_barrier
	s_add_i32 s22, s26, s36
	v_lshl_add_u64 v[214:215], v[218:219], 0, s[44:45]
	s_mov_b32 m0, s22
	ds_read_b128 v[180:183], v175 offset:49152
	ds_read_b128 v[184:187], v175 offset:50176
	ds_read_b128 v[188:191], v175 offset:51200
	ds_read_b128 v[192:195], v175 offset:52224
	ds_read_b128 v[196:199], v175 offset:53248
	ds_read_b128 v[200:203], v175 offset:54272
	ds_read_b128 v[204:207], v175 offset:55296
	ds_read_b128 v[208:211], v175 offset:56320
	global_load_lds_dwordx4 v[214:215], off
	v_lshl_add_u64 v[214:215], v[220:221], 0, s[44:45]
	s_add_i32 m0, s22, 0x2000
	s_add_i32 s22, s27, s36
	global_load_lds_dwordx4 v[214:215], off
	v_lshl_add_u64 v[214:215], v[222:223], 0, s[44:45]
	s_mov_b32 m0, s22
	s_nop 0
	global_load_lds_dwordx4 v[214:215], off
	v_lshl_add_u64 v[214:215], v[224:225], 0, s[44:45]
	s_add_i32 m0, s22, 0x2000
	s_nop 0
	global_load_lds_dwordx4 v[214:215], off
	v_lshl_add_u64 v[214:215], v[226:227], 0, s[44:45]
	s_mov_b32 m0, s50
	s_nop 0
	global_load_lds_dwordx4 v[214:215], off
	v_lshl_add_u64 v[214:215], v[228:229], 0, s[44:45]
	s_mov_b32 m0, s51
	s_nop 0
	global_load_lds_dwordx4 v[214:215], off
	s_waitcnt vmcnt(8) lgkmcnt(0)
	s_barrier
	s_setprio 1
	v_mfma_f32_16x16x32_bf16 v[60:63], v[132:135], v[180:183], v[60:63]
	v_mfma_f32_16x16x32_bf16 v[56:59], v[140:143], v[180:183], v[56:59]
	v_mfma_f32_16x16x32_bf16 v[48:51], v[132:135], v[188:191], v[48:51]
	v_mfma_f32_16x16x32_bf16 v[40:43], v[140:143], v[188:191], v[40:43]
	v_mfma_f32_16x16x32_bf16 v[32:35], v[132:135], v[196:199], v[32:35]
	v_mfma_f32_16x16x32_bf16 v[24:27], v[140:143], v[196:199], v[24:27]
	v_mfma_f32_16x16x32_bf16 v[16:19], v[132:135], v[204:207], v[16:19]
	v_mfma_f32_16x16x32_bf16 v[8:11], v[140:143], v[204:207], v[8:11]
	v_mfma_f32_16x16x32_bf16 v[60:63], v[136:139], v[184:187], v[60:63]
	v_mfma_f32_16x16x32_bf16 v[56:59], v[144:147], v[184:187], v[56:59]
	v_mfma_f32_16x16x32_bf16 v[48:51], v[136:139], v[192:195], v[48:51]
	v_mfma_f32_16x16x32_bf16 v[40:43], v[144:147], v[192:195], v[40:43]
	v_mfma_f32_16x16x32_bf16 v[32:35], v[136:139], v[200:203], v[32:35]
	v_mfma_f32_16x16x32_bf16 v[24:27], v[144:147], v[200:203], v[24:27]
	v_mfma_f32_16x16x32_bf16 v[16:19], v[136:139], v[208:211], v[16:19]
	v_mfma_f32_16x16x32_bf16 v[8:11], v[144:147], v[208:211], v[8:11]
	s_setprio 0
	s_setprio 1
	v_mfma_f32_16x16x32_bf16 v[52:55], v[154:157], v[180:183], v[52:55]
	v_mfma_f32_16x16x32_bf16 v[44:47], v[162:165], v[180:183], v[44:47]
	v_mfma_f32_16x16x32_bf16 v[36:39], v[154:157], v[188:191], v[36:39]
	v_mfma_f32_16x16x32_bf16 v[28:31], v[162:165], v[188:191], v[28:31]
	v_mfma_f32_16x16x32_bf16 v[20:23], v[154:157], v[196:199], v[20:23]
	v_mfma_f32_16x16x32_bf16 v[12:15], v[162:165], v[196:199], v[12:15]
	v_mfma_f32_16x16x32_bf16 v[4:7], v[154:157], v[204:207], v[4:7]
	v_mfma_f32_16x16x32_bf16 v[0:3], v[162:165], v[204:207], v[0:3]
	v_mfma_f32_16x16x32_bf16 v[52:55], v[158:161], v[184:187], v[52:55]
	v_mfma_f32_16x16x32_bf16 v[44:47], v[176:179], v[184:187], v[44:47]
	v_mfma_f32_16x16x32_bf16 v[36:39], v[158:161], v[192:195], v[36:39]
	v_mfma_f32_16x16x32_bf16 v[28:31], v[176:179], v[192:195], v[28:31]
	v_mfma_f32_16x16x32_bf16 v[20:23], v[158:161], v[200:203], v[20:23]
	v_mfma_f32_16x16x32_bf16 v[12:15], v[176:179], v[200:203], v[12:15]
	v_mfma_f32_16x16x32_bf16 v[4:7], v[158:161], v[208:211], v[4:7]
	v_mfma_f32_16x16x32_bf16 v[0:3], v[176:179], v[208:211], v[0:3]
	s_setprio 0
	s_barrier
	s_cmp_ge_u32 s60, s48
	s_cbranch_scc1 .LBB0_736
	s_mov_b64 s[22:23], s[24:25]
	v_mov_b32_e32 v132, v171
	v_mov_b32_e32 v133, v170
	s_branch .LBB0_732

.LBB0_957:
	s_ashr_i32 s21, s20, 31
	s_lshl_b64 s[30:31], s[20:21], 18
	s_add_u32 s30, s78, s30
	s_addc_u32 s31, s79, s31
	s_and_b64 s[36:37], s[24:25], exec
	s_cselect_b32 s9, s31, s23
	s_cselect_b32 s21, s30, s22
	s_ashr_i32 s27, s26, 31
	s_lshl_b64 s[26:27], s[26:27], 13
	s_add_u32 s29, s50, s26
	s_addc_u32 s35, s51, s27
	s_lshl_b32 s36, s28, 7
	s_ashr_i32 s37, s36, 31
	s_lshl_b64 s[26:27], s[36:37], 2
	s_add_u32 s26, s29, s26
	s_addc_u32 s27, s35, s27
	s_lshl_b32 s28, s67, 2
	s_add_u32 s26, s26, s28
	s_addc_u32 s27, s27, 0
	v_mov_b32_e32 v183, v213
	s_add_i32 s62, 0, 0x14000
	s_add_i32 s60, 0, 0x10000
	v_lshl_add_u64 v[184:185], s[26:27], 0, v[182:183]
	v_add_u32_e32 v183, s62, v201
	v_add_u32_e32 v204, s60, v201
	ds_read_b128 v[0:3], v183
	ds_read_b128 v[4:7], v183 offset:1024
	ds_read_b128 v[8:11], v183 offset:2048
	ds_read_b128 v[12:15], v183 offset:3072
	ds_read_b128 v[20:23], v204 offset:3072
	ds_read_b128 v[16:19], v204 offset:2048
	ds_read_b128 v[28:31], v204 offset:1024
	ds_read_b128 v[24:27], v204
	s_mov_b64 s[26:27], 0x1000
	v_lshl_add_u64 v[186:187], v[184:185], 0, s[26:27]
	s_lshl_b32 s26, s57, 10
	s_add_i32 s26, s26, 0
	s_add_i32 s26, s26, 0x20d00
	v_add3_u32 v205, s26, v211, v234
	v_add3_u32 v206, s26, v196, v197
	s_add_i32 s37, s40, 0xc000
	s_mov_b32 m0, s37
	s_add_i32 s59, s40, 0xe000
	ds_read_b128 v[48:51], v203
	ds_read_b128 v[52:55], v203 offset:1024
	ds_read_b128 v[56:59], v203 offset:2048
	ds_read_b128 v[60:63], v203 offset:3072
	ds_read_b128 v[64:67], v203 offset:4096
	ds_read_b128 v[68:71], v203 offset:5120
	ds_read_b128 v[72:75], v203 offset:6144
	ds_read_b128 v[76:79], v203 offset:7168
	global_load_lds_dwordx4 v198, s[88:89]
	s_mov_b32 m0, s59
	s_nop 0
	global_load_lds_dwordx4 v199, s[88:89]
	s_waitcnt vmcnt(8) lgkmcnt(0)
	s_barrier
	s_setprio 1
	v_mfma_scale_f32_16x16x128_f8f6f4 v[164:167], v[24:31], v[48:55], 0, v232, v232 op_sel_hi:[0,0,0]
	v_mfma_scale_f32_16x16x128_f8f6f4 v[160:163], v[16:23], v[48:55], 0, v232, v232 op_sel_hi:[0,0,0]
	v_mfma_scale_f32_16x16x128_f8f6f4 v[148:151], v[24:31], v[56:63], 0, v232, v232 op_sel_hi:[0,0,0]
	v_mfma_scale_f32_16x16x128_f8f6f4 v[144:147], v[16:23], v[56:63], 0, v232, v232 op_sel_hi:[0,0,0]
	v_mfma_scale_f32_16x16x128_f8f6f4 v[132:135], v[24:31], v[64:71], 0, v232, v232 op_sel_hi:[0,0,0]
	v_mfma_scale_f32_16x16x128_f8f6f4 v[128:131], v[16:23], v[64:71], 0, v232, v232 op_sel_hi:[0,0,0]
	v_mfma_scale_f32_16x16x128_f8f6f4 v[116:119], v[24:31], v[72:79], 0, v232, v232 op_sel_hi:[0,0,0]
	v_mfma_scale_f32_16x16x128_f8f6f4 v[112:115], v[16:23], v[72:79], 0, v232, v232 op_sel_hi:[0,0,0]
	s_setprio 0
	s_setprio 1
	v_mfma_scale_f32_16x16x128_f8f6f4 v[168:171], v[0:7], v[48:55], 0, v232, v232 op_sel_hi:[0,0,0]
	v_mfma_scale_f32_16x16x128_f8f6f4 v[172:175], v[8:15], v[48:55], 0, v232, v232 op_sel_hi:[0,0,0]
	v_mfma_scale_f32_16x16x128_f8f6f4 v[156:159], v[0:7], v[56:63], 0, v232, v232 op_sel_hi:[0,0,0]
	v_mfma_scale_f32_16x16x128_f8f6f4 v[152:155], v[8:15], v[56:63], 0, v232, v232 op_sel_hi:[0,0,0]
	v_mfma_scale_f32_16x16x128_f8f6f4 v[140:143], v[0:7], v[64:71], 0, v232, v232 op_sel_hi:[0,0,0]
	v_mfma_scale_f32_16x16x128_f8f6f4 v[136:139], v[8:15], v[64:71], 0, v232, v232 op_sel_hi:[0,0,0]
	v_mfma_scale_f32_16x16x128_f8f6f4 v[124:127], v[0:7], v[72:79], 0, v232, v232 op_sel_hi:[0,0,0]
	v_mfma_scale_f32_16x16x128_f8f6f4 v[120:123], v[8:15], v[72:79], 0, v232, v232 op_sel_hi:[0,0,0]
	s_setprio 0
	s_barrier
	s_add_i32 s60, s60, s66
	v_lshl_add_u64 v[188:189], s[22:23], 0, v[176:177]
	s_add_i32 s61, s60, 0x2000
	v_lshl_add_u64 v[48:49], v[188:189], 0, s[46:47]
	s_mov_b32 m0, s60
	v_lshl_add_u64 v[190:191], s[22:23], 0, v[178:179]
	s_add_u32 s26, s22, 0x20100
	ds_read_b128 v[56:59], v203 offset:16384
	ds_read_b128 v[60:63], v203 offset:17408
	ds_read_b128 v[72:75], v203 offset:18432
	ds_read_b128 v[76:79], v203 offset:19456
	ds_read_b128 v[214:217], v203 offset:20480
	ds_read_b128 v[218:221], v203 offset:21504
	ds_read_b128 v[238:241], v203 offset:22528
	ds_read_b128 v[242:245], v203 offset:23552
	global_load_lds_dwordx4 v[48:49], off
	v_lshl_add_u64 v[48:49], v[190:191], 0, s[46:47]
	s_mov_b32 m0, s61
	s_addc_u32 s27, s23, 0
	s_add_i32 s62, s62, s66
	global_load_lds_dwordx4 v[48:49], off
	v_lshl_add_u64 v[48:49], s[26:27], 0, v[176:177]
	s_mov_b32 m0, s62
	s_add_i32 s63, s62, 0x2000
	global_load_lds_dwordx4 v[48:49], off
	v_lshl_add_u64 v[48:49], s[26:27], 0, v[178:179]
	s_mov_b32 m0, s63
	s_nop 0
	global_load_lds_dwordx4 v[48:49], off
	s_mov_b32 m0, s40
	s_nop 0
	global_load_lds_dwordx4 v212, s[92:93]
	s_mov_b32 m0, s41
	s_nop 0
	global_load_lds_dwordx4 v180, s[92:93]
	s_waitcnt vmcnt(8) lgkmcnt(0)
	s_barrier
	s_setprio 1
	v_mfma_scale_f32_16x16x128_f8f6f4 v[100:103], v[24:31], v[56:63], 0, v232, v232 op_sel_hi:[0,0,0]
	v_mfma_scale_f32_16x16x128_f8f6f4 v[96:99], v[16:23], v[56:63], 0, v232, v232 op_sel_hi:[0,0,0]
	v_mfma_scale_f32_16x16x128_f8f6f4 v[84:87], v[24:31], v[72:79], 0, v232, v232 op_sel_hi:[0,0,0]
	v_mfma_scale_f32_16x16x128_f8f6f4 v[80:83], v[16:23], v[72:79], 0, v232, v232 op_sel_hi:[0,0,0]
	v_mfma_scale_f32_16x16x128_f8f6f4 v[68:71], v[24:31], v[214:221], 0, v232, v232 op_sel_hi:[0,0,0]
	v_mfma_scale_f32_16x16x128_f8f6f4 v[64:67], v[16:23], v[214:221], 0, v232, v232 op_sel_hi:[0,0,0]
	v_mfma_scale_f32_16x16x128_f8f6f4 v[52:55], v[24:31], v[238:245], 0, v232, v232 op_sel_hi:[0,0,0]
	v_mfma_scale_f32_16x16x128_f8f6f4 v[48:51], v[16:23], v[238:245], 0, v232, v232 op_sel_hi:[0,0,0]
	s_setprio 0
	s_setprio 1
	v_mfma_scale_f32_16x16x128_f8f6f4 v[108:111], v[0:7], v[56:63], 0, v232, v232 op_sel_hi:[0,0,0]
	v_mfma_scale_f32_16x16x128_f8f6f4 v[104:107], v[8:15], v[56:63], 0, v232, v232 op_sel_hi:[0,0,0]
	v_mfma_scale_f32_16x16x128_f8f6f4 v[92:95], v[0:7], v[72:79], 0, v232, v232 op_sel_hi:[0,0,0]
	v_mfma_scale_f32_16x16x128_f8f6f4 v[88:91], v[8:15], v[72:79], 0, v232, v232 op_sel_hi:[0,0,0]
	v_mfma_scale_f32_16x16x128_f8f6f4 v[76:79], v[0:7], v[214:221], 0, v232, v232 op_sel_hi:[0,0,0]
	v_mfma_scale_f32_16x16x128_f8f6f4 v[72:75], v[8:15], v[214:221], 0, v232, v232 op_sel_hi:[0,0,0]
	v_mfma_scale_f32_16x16x128_f8f6f4 v[60:63], v[0:7], v[238:245], 0, v232, v232 op_sel_hi:[0,0,0]
	v_mfma_scale_f32_16x16x128_f8f6f4 v[56:59], v[8:15], v[238:245], 0, v232, v232 op_sel_hi:[0,0,0]
	s_setprio 0
	s_barrier
	s_add_i32 s64, 0, 0x18000
	s_add_i32 s68, 0, 0x1c000
	v_add_u32_e32 v207, s64, v201
	v_add_u32_e32 v208, s68, v201
	ds_read_b128 v[24:27], v207
	ds_read_b128 v[28:31], v207 offset:1024
	ds_read_b128 v[16:19], v207 offset:2048
	ds_read_b128 v[20:23], v207 offset:3072
	ds_read_b128 v[8:11], v208
	ds_read_b128 v[12:15], v208 offset:1024
	ds_read_b128 v[0:3], v208 offset:2048
	ds_read_b128 v[4:7], v208 offset:3072
	s_mov_b32 m0, s48
	ds_read_b128 v[214:217], v203 offset:32768
	ds_read_b128 v[218:221], v203 offset:33792
	ds_read_b128 v[238:241], v203 offset:34816
	ds_read_b128 v[242:245], v203 offset:35840
	ds_read_b128 v[246:249], v203 offset:36864
	ds_read_b128 v[250:253], v203 offset:37888
	ds_read_b128 v[222:225], v203 offset:38912
	ds_read_b128 v[226:229], v203 offset:39936
	global_load_lds_dwordx4 v198, s[92:93]
	s_mov_b32 m0, s49
	s_nop 0
	global_load_lds_dwordx4 v199, s[92:93]
	s_waitcnt vmcnt(8) lgkmcnt(0)
	s_barrier
	s_setprio 1
	v_mfma_scale_f32_16x16x128_f8f6f4 v[164:167], v[24:31], v[214:221], v[164:167], v232, v232 op_sel_hi:[0,0,0]
	v_mfma_scale_f32_16x16x128_f8f6f4 v[160:163], v[16:23], v[214:221], v[160:163], v232, v232 op_sel_hi:[0,0,0]
	v_mfma_scale_f32_16x16x128_f8f6f4 v[148:151], v[24:31], v[238:245], v[148:151], v232, v232 op_sel_hi:[0,0,0]
	v_mfma_scale_f32_16x16x128_f8f6f4 v[144:147], v[16:23], v[238:245], v[144:147], v232, v232 op_sel_hi:[0,0,0]
	v_mfma_scale_f32_16x16x128_f8f6f4 v[132:135], v[24:31], v[246:253], v[132:135], v232, v232 op_sel_hi:[0,0,0]
	v_mfma_scale_f32_16x16x128_f8f6f4 v[128:131], v[16:23], v[246:253], v[128:131], v232, v232 op_sel_hi:[0,0,0]
	v_mfma_scale_f32_16x16x128_f8f6f4 v[116:119], v[24:31], v[222:229], v[116:119], v232, v232 op_sel_hi:[0,0,0]
	v_mfma_scale_f32_16x16x128_f8f6f4 v[112:115], v[16:23], v[222:229], v[112:115], v232, v232 op_sel_hi:[0,0,0]
	s_setprio 0
	s_setprio 1
	v_mfma_scale_f32_16x16x128_f8f6f4 v[168:171], v[8:15], v[214:221], v[168:171], v232, v232 op_sel_hi:[0,0,0]
	v_mfma_scale_f32_16x16x128_f8f6f4 v[172:175], v[0:7], v[214:221], v[172:175], v232, v232 op_sel_hi:[0,0,0]
	v_mfma_scale_f32_16x16x128_f8f6f4 v[156:159], v[8:15], v[238:245], v[156:159], v232, v232 op_sel_hi:[0,0,0]
	v_mfma_scale_f32_16x16x128_f8f6f4 v[152:155], v[0:7], v[238:245], v[152:155], v232, v232 op_sel_hi:[0,0,0]
	v_mfma_scale_f32_16x16x128_f8f6f4 v[140:143], v[8:15], v[246:253], v[140:143], v232, v232 op_sel_hi:[0,0,0]
	v_mfma_scale_f32_16x16x128_f8f6f4 v[136:139], v[0:7], v[246:253], v[136:139], v232, v232 op_sel_hi:[0,0,0]
	v_mfma_scale_f32_16x16x128_f8f6f4 v[124:127], v[8:15], v[222:229], v[124:127], v232, v232 op_sel_hi:[0,0,0]
	v_mfma_scale_f32_16x16x128_f8f6f4 v[120:123], v[0:7], v[222:229], v[120:123], v232, v232 op_sel_hi:[0,0,0]
	s_setprio 0
	s_barrier
	s_add_i32 s64, s64, s66
	s_add_i32 s65, s64, 0x2000
	v_lshl_add_u64 v[188:189], v[188:189], 0, s[84:85]
	s_mov_b32 m0, s64
	s_add_u32 s26, s22, 0x20180
	ds_read_b128 v[214:217], v203 offset:49152
	ds_read_b128 v[218:221], v203 offset:50176
	ds_read_b128 v[222:225], v203 offset:51200
	ds_read_b128 v[226:229], v203 offset:52224
	ds_read_b128 v[238:241], v203 offset:53248
	ds_read_b128 v[242:245], v203 offset:54272
	ds_read_b128 v[246:249], v203 offset:55296
	ds_read_b128 v[250:253], v203 offset:56320
	global_load_lds_dwordx4 v[188:189], off
	v_lshl_add_u64 v[188:189], v[190:191], 0, s[84:85]
	s_mov_b32 m0, s65
	s_addc_u32 s27, s23, 0
	s_add_i32 s68, s68, s66
	global_load_lds_dwordx4 v[188:189], off
	v_lshl_add_u64 v[188:189], s[26:27], 0, v[176:177]
	s_mov_b32 m0, s68
	s_add_i32 s69, s68, 0x2000
	global_load_lds_dwordx4 v[188:189], off
	v_lshl_add_u64 v[188:189], s[26:27], 0, v[178:179]
	s_mov_b32 m0, s69
	s_nop 0
	global_load_lds_dwordx4 v[188:189], off
	s_mov_b32 m0, s52
	s_nop 0
	global_load_lds_dwordx4 v212, s[94:95]
	s_mov_b32 m0, s53
	s_nop 0
	global_load_lds_dwordx4 v180, s[94:95]
	s_waitcnt vmcnt(8) lgkmcnt(0)
	s_barrier
	s_setprio 1
	v_mfma_scale_f32_16x16x128_f8f6f4 v[100:103], v[24:31], v[214:221], v[100:103], v232, v232 op_sel_hi:[0,0,0]
	v_mfma_scale_f32_16x16x128_f8f6f4 v[96:99], v[16:23], v[214:221], v[96:99], v232, v232 op_sel_hi:[0,0,0]
	v_mfma_scale_f32_16x16x128_f8f6f4 v[84:87], v[24:31], v[222:229], v[84:87], v232, v232 op_sel_hi:[0,0,0]
	v_mfma_scale_f32_16x16x128_f8f6f4 v[80:83], v[16:23], v[222:229], v[80:83], v232, v232 op_sel_hi:[0,0,0]
	v_mfma_scale_f32_16x16x128_f8f6f4 v[68:71], v[24:31], v[238:245], v[68:71], v232, v232 op_sel_hi:[0,0,0]
	v_mfma_scale_f32_16x16x128_f8f6f4 v[64:67], v[16:23], v[238:245], v[64:67], v232, v232 op_sel_hi:[0,0,0]
	v_mfma_scale_f32_16x16x128_f8f6f4 v[52:55], v[24:31], v[246:253], v[52:55], v232, v232 op_sel_hi:[0,0,0]
	v_mfma_scale_f32_16x16x128_f8f6f4 v[48:51], v[16:23], v[246:253], v[48:51], v232, v232 op_sel_hi:[0,0,0]
	s_setprio 0
	s_setprio 1
	v_mfma_scale_f32_16x16x128_f8f6f4 v[108:111], v[8:15], v[214:221], v[108:111], v232, v232 op_sel_hi:[0,0,0]
	v_mfma_scale_f32_16x16x128_f8f6f4 v[104:107], v[0:7], v[214:221], v[104:107], v232, v232 op_sel_hi:[0,0,0]
	v_mfma_scale_f32_16x16x128_f8f6f4 v[92:95], v[8:15], v[222:229], v[92:95], v232, v232 op_sel_hi:[0,0,0]
	v_mfma_scale_f32_16x16x128_f8f6f4 v[88:91], v[0:7], v[222:229], v[88:91], v232, v232 op_sel_hi:[0,0,0]
	v_mfma_scale_f32_16x16x128_f8f6f4 v[76:79], v[8:15], v[238:245], v[76:79], v232, v232 op_sel_hi:[0,0,0]
	v_mfma_scale_f32_16x16x128_f8f6f4 v[72:75], v[0:7], v[238:245], v[72:75], v232, v232 op_sel_hi:[0,0,0]
	v_mfma_scale_f32_16x16x128_f8f6f4 v[60:63], v[8:15], v[246:253], v[60:63], v232, v232 op_sel_hi:[0,0,0]
	v_mfma_scale_f32_16x16x128_f8f6f4 v[56:59], v[0:7], v[246:253], v[56:59], v232, v232 op_sel_hi:[0,0,0]
	s_setprio 0
	s_barrier
	s_add_u32 s70, s22, 0x200
	s_addc_u32 s71, s23, 0
	s_mov_b32 s82, 0
	s_mov_b64 s[22:23], 0
	s_branch .LBB0_959
.LBB0_958:
	ds_read_b128 v[24:27], v204
	ds_read_b128 v[28:31], v204 offset:1024
	ds_read_b128 v[214:217], v204 offset:2048
	ds_read_b128 v[218:221], v204 offset:3072
	ds_read_b128 v[8:11], v183
	ds_read_b128 v[12:15], v183 offset:1024
	ds_read_b128 v[0:3], v183 offset:2048
	ds_read_b128 v[4:7], v183 offset:3072
	s_add_u32 s35, s22, 0x200
	s_addc_u32 vcc_lo, s23, 0
	s_and_b64 s[28:29], s[26:27], exec
	s_cselect_b32 vcc_lo, 0, vcc_lo
	s_cselect_b32 s35, 0, s35
	s_add_u32 s28, s70, s22
	s_addc_u32 s29, s71, s23
	s_and_b64 s[26:27], s[26:27], exec
	s_cselect_b32 s27, s9, s29
	s_cselect_b32 s26, s21, s28
	s_add_u32 s28, s94, s22
	s_addc_u32 s29, s95, s23
	s_mov_b32 m0, s37
	ds_read_b128 v[222:225], v203
	ds_read_b128 v[226:229], v203 offset:1024
	ds_read_b128 v[238:241], v203 offset:2048
	ds_read_b128 v[242:245], v203 offset:3072
	ds_read_b128 v[246:249], v203 offset:4096
	ds_read_b128 v[250:253], v203 offset:5120
	ds_read_b128 v[188:191], v203 offset:6144
	ds_read_b128 v[192:195], v203 offset:7168
	global_load_lds_dwordx4 v17, s[28:29]
	s_mov_b32 m0, s59
	s_nop 0
	global_load_lds_dwordx4 v16, s[28:29]
	s_waitcnt vmcnt(8) lgkmcnt(0)
	s_barrier
	s_setprio 1
	v_mfma_scale_f32_16x16x128_f8f6f4 v[164:167], v[24:31], v[222:229], v[164:167], v232, v232 op_sel_hi:[0,0,0]
	v_mfma_scale_f32_16x16x128_f8f6f4 v[160:163], v[214:221], v[222:229], v[160:163], v232, v232 op_sel_hi:[0,0,0]
	v_mfma_scale_f32_16x16x128_f8f6f4 v[148:151], v[24:31], v[238:245], v[148:151], v232, v232 op_sel_hi:[0,0,0]
	v_mfma_scale_f32_16x16x128_f8f6f4 v[144:147], v[214:221], v[238:245], v[144:147], v232, v232 op_sel_hi:[0,0,0]
	v_mfma_scale_f32_16x16x128_f8f6f4 v[132:135], v[24:31], v[246:253], v[132:135], v232, v232 op_sel_hi:[0,0,0]
	v_mfma_scale_f32_16x16x128_f8f6f4 v[128:131], v[214:221], v[246:253], v[128:131], v232, v232 op_sel_hi:[0,0,0]
	v_mfma_scale_f32_16x16x128_f8f6f4 v[116:119], v[24:31], v[188:195], v[116:119], v232, v232 op_sel_hi:[0,0,0]
	v_mfma_scale_f32_16x16x128_f8f6f4 v[112:115], v[214:221], v[188:195], v[112:115], v232, v232 op_sel_hi:[0,0,0]
	s_setprio 0
	s_setprio 1
	v_mfma_scale_f32_16x16x128_f8f6f4 v[168:171], v[8:15], v[222:229], v[168:171], v232, v232 op_sel_hi:[0,0,0]
	v_mfma_scale_f32_16x16x128_f8f6f4 v[172:175], v[0:7], v[222:229], v[172:175], v232, v232 op_sel_hi:[0,0,0]
	v_mfma_scale_f32_16x16x128_f8f6f4 v[156:159], v[8:15], v[238:245], v[156:159], v232, v232 op_sel_hi:[0,0,0]
	v_mfma_scale_f32_16x16x128_f8f6f4 v[152:155], v[0:7], v[238:245], v[152:155], v232, v232 op_sel_hi:[0,0,0]
	v_mfma_scale_f32_16x16x128_f8f6f4 v[140:143], v[8:15], v[246:253], v[140:143], v232, v232 op_sel_hi:[0,0,0]
	v_mfma_scale_f32_16x16x128_f8f6f4 v[136:139], v[0:7], v[246:253], v[136:139], v232, v232 op_sel_hi:[0,0,0]
	v_mfma_scale_f32_16x16x128_f8f6f4 v[124:127], v[8:15], v[188:195], v[124:127], v232, v232 op_sel_hi:[0,0,0]
	v_mfma_scale_f32_16x16x128_f8f6f4 v[120:123], v[0:7], v[188:195], v[120:123], v232, v232 op_sel_hi:[0,0,0]
	s_setprio 0
	s_barrier
	s_mov_b32 m0, s60
	v_lshl_add_u64 v[16:17], s[26:27], 0, v[176:177]
	s_add_u32 s28, s26, 0x20000
	ds_read_b128 v[188:191], v203 offset:16384
	ds_read_b128 v[192:195], v203 offset:17408
	ds_read_b128 v[222:225], v203 offset:18432
	ds_read_b128 v[226:229], v203 offset:19456
	ds_read_b128 v[238:241], v203 offset:20480
	ds_read_b128 v[242:245], v203 offset:21504
	ds_read_b128 v[246:249], v203 offset:22528
	ds_read_b128 v[250:253], v203 offset:23552
	global_load_lds_dwordx4 v[16:17], off
	v_lshl_add_u64 v[18:19], s[26:27], 0, v[178:179]
	s_mov_b32 m0, s61
	s_addc_u32 s29, s27, 0
	global_load_lds_dwordx4 v[18:19], off
	v_lshl_add_u64 v[20:21], s[28:29], 0, v[176:177]
	s_mov_b32 m0, s62
	v_mov_b32_e32 v181, v213
	global_load_lds_dwordx4 v[20:21], off
	v_lshl_add_u64 v[20:21], s[28:29], 0, v[178:179]
	s_mov_b32 m0, s63
	s_add_u32 s28, s12, s35
	global_load_lds_dwordx4 v[20:21], off
	s_addc_u32 s29, s13, vcc_lo
	s_mov_b32 m0, s40
	v_lshl_add_u64 v[22:23], s[28:29], 0, v[212:213]
	global_load_lds_dwordx4 v212, s[28:29]
	s_mov_b32 m0, s41
	v_lshl_add_u64 v[20:21], s[28:29], 0, v[180:181]
	global_load_lds_dwordx4 v180, s[28:29]
	s_waitcnt vmcnt(8) lgkmcnt(0)
	s_barrier
	s_setprio 1
	v_mfma_scale_f32_16x16x128_f8f6f4 v[100:103], v[24:31], v[188:195], v[100:103], v232, v232 op_sel_hi:[0,0,0]
	v_mfma_scale_f32_16x16x128_f8f6f4 v[96:99], v[214:221], v[188:195], v[96:99], v232, v232 op_sel_hi:[0,0,0]
	v_mfma_scale_f32_16x16x128_f8f6f4 v[84:87], v[24:31], v[222:229], v[84:87], v232, v232 op_sel_hi:[0,0,0]
	v_mfma_scale_f32_16x16x128_f8f6f4 v[80:83], v[214:221], v[222:229], v[80:83], v232, v232 op_sel_hi:[0,0,0]
	v_mfma_scale_f32_16x16x128_f8f6f4 v[68:71], v[24:31], v[238:245], v[68:71], v232, v232 op_sel_hi:[0,0,0]
	v_mfma_scale_f32_16x16x128_f8f6f4 v[64:67], v[214:221], v[238:245], v[64:67], v232, v232 op_sel_hi:[0,0,0]
	v_mfma_scale_f32_16x16x128_f8f6f4 v[52:55], v[24:31], v[246:253], v[52:55], v232, v232 op_sel_hi:[0,0,0]
	v_mfma_scale_f32_16x16x128_f8f6f4 v[48:51], v[214:221], v[246:253], v[48:51], v232, v232 op_sel_hi:[0,0,0]
	s_setprio 0
	s_setprio 1
	v_mfma_scale_f32_16x16x128_f8f6f4 v[108:111], v[8:15], v[188:195], v[108:111], v232, v232 op_sel_hi:[0,0,0]
	v_mfma_scale_f32_16x16x128_f8f6f4 v[104:107], v[0:7], v[188:195], v[104:107], v232, v232 op_sel_hi:[0,0,0]
	v_mfma_scale_f32_16x16x128_f8f6f4 v[92:95], v[8:15], v[222:229], v[92:95], v232, v232 op_sel_hi:[0,0,0]
	v_mfma_scale_f32_16x16x128_f8f6f4 v[88:91], v[0:7], v[222:229], v[88:91], v232, v232 op_sel_hi:[0,0,0]
	v_mfma_scale_f32_16x16x128_f8f6f4 v[76:79], v[8:15], v[238:245], v[76:79], v232, v232 op_sel_hi:[0,0,0]
	v_mfma_scale_f32_16x16x128_f8f6f4 v[72:75], v[0:7], v[238:245], v[72:75], v232, v232 op_sel_hi:[0,0,0]
	v_mfma_scale_f32_16x16x128_f8f6f4 v[60:63], v[8:15], v[246:253], v[60:63], v232, v232 op_sel_hi:[0,0,0]
	v_mfma_scale_f32_16x16x128_f8f6f4 v[56:59], v[0:7], v[246:253], v[56:59], v232, v232 op_sel_hi:[0,0,0]
	s_setprio 0
	s_barrier
	ds_read_b128 v[24:27], v207
	ds_read_b128 v[28:31], v207 offset:1024
	ds_read_b128 v[188:191], v207 offset:2048
	ds_read_b128 v[192:195], v207 offset:3072
	ds_read_b128 v[8:11], v208
	ds_read_b128 v[12:15], v208 offset:1024
	ds_read_b128 v[0:3], v208 offset:2048
	ds_read_b128 v[4:7], v208 offset:3072
	s_mov_b32 m0, s48
	ds_read_b128 v[214:217], v203 offset:32768
	ds_read_b128 v[218:221], v203 offset:33792
	ds_read_b128 v[222:225], v203 offset:34816
	ds_read_b128 v[226:229], v203 offset:35840
	ds_read_b128 v[238:241], v203 offset:36864
	ds_read_b128 v[242:245], v203 offset:37888
	ds_read_b128 v[246:249], v203 offset:38912
	ds_read_b128 v[250:253], v203 offset:39936
	global_load_lds_dwordx4 v198, s[28:29]
	s_mov_b32 m0, s49
	s_nop 0
	global_load_lds_dwordx4 v199, s[28:29]
	s_waitcnt vmcnt(8) lgkmcnt(0)
	s_barrier
	s_setprio 1
	v_mfma_scale_f32_16x16x128_f8f6f4 v[164:167], v[24:31], v[214:221], v[164:167], v232, v232 op_sel_hi:[0,0,0]
	v_mfma_scale_f32_16x16x128_f8f6f4 v[160:163], v[188:195], v[214:221], v[160:163], v232, v232 op_sel_hi:[0,0,0]
	v_mfma_scale_f32_16x16x128_f8f6f4 v[148:151], v[24:31], v[222:229], v[148:151], v232, v232 op_sel_hi:[0,0,0]
	v_mfma_scale_f32_16x16x128_f8f6f4 v[144:147], v[188:195], v[222:229], v[144:147], v232, v232 op_sel_hi:[0,0,0]
	v_mfma_scale_f32_16x16x128_f8f6f4 v[132:135], v[24:31], v[238:245], v[132:135], v232, v232 op_sel_hi:[0,0,0]
	v_mfma_scale_f32_16x16x128_f8f6f4 v[128:131], v[188:195], v[238:245], v[128:131], v232, v232 op_sel_hi:[0,0,0]
	v_mfma_scale_f32_16x16x128_f8f6f4 v[116:119], v[24:31], v[246:253], v[116:119], v232, v232 op_sel_hi:[0,0,0]
	v_mfma_scale_f32_16x16x128_f8f6f4 v[112:115], v[188:195], v[246:253], v[112:115], v232, v232 op_sel_hi:[0,0,0]
	s_setprio 0
	s_setprio 1
	v_mfma_scale_f32_16x16x128_f8f6f4 v[168:171], v[8:15], v[214:221], v[168:171], v232, v232 op_sel_hi:[0,0,0]
	v_mfma_scale_f32_16x16x128_f8f6f4 v[172:175], v[0:7], v[214:221], v[172:175], v232, v232 op_sel_hi:[0,0,0]
	v_mfma_scale_f32_16x16x128_f8f6f4 v[156:159], v[8:15], v[222:229], v[156:159], v232, v232 op_sel_hi:[0,0,0]
	v_mfma_scale_f32_16x16x128_f8f6f4 v[152:155], v[0:7], v[222:229], v[152:155], v232, v232 op_sel_hi:[0,0,0]
	v_mfma_scale_f32_16x16x128_f8f6f4 v[140:143], v[8:15], v[238:245], v[140:143], v232, v232 op_sel_hi:[0,0,0]
	v_mfma_scale_f32_16x16x128_f8f6f4 v[136:139], v[0:7], v[238:245], v[136:139], v232, v232 op_sel_hi:[0,0,0]
	v_mfma_scale_f32_16x16x128_f8f6f4 v[124:127], v[8:15], v[246:253], v[124:127], v232, v232 op_sel_hi:[0,0,0]
	v_mfma_scale_f32_16x16x128_f8f6f4 v[120:123], v[0:7], v[246:253], v[120:123], v232, v232 op_sel_hi:[0,0,0]
	s_setprio 0
	s_barrier
	s_mov_b32 m0, s64
	v_lshl_add_u64 v[16:17], v[16:17], 0, s[44:45]
	s_add_u32 s26, s26, 0x20080
	ds_read_b128 v[214:217], v203 offset:49152
	ds_read_b128 v[218:221], v203 offset:50176
	ds_read_b128 v[222:225], v203 offset:51200
	ds_read_b128 v[226:229], v203 offset:52224
	ds_read_b128 v[238:241], v203 offset:53248
	ds_read_b128 v[242:245], v203 offset:54272
	ds_read_b128 v[246:249], v203 offset:55296
	ds_read_b128 v[250:253], v203 offset:56320
	global_load_lds_dwordx4 v[16:17], off
	v_lshl_add_u64 v[16:17], v[18:19], 0, s[44:45]
	s_mov_b32 m0, s65
	s_addc_u32 s27, s27, 0
	global_load_lds_dwordx4 v[16:17], off
	v_lshl_add_u64 v[16:17], s[26:27], 0, v[176:177]
	s_mov_b32 m0, s68
	s_nop 0
	global_load_lds_dwordx4 v[16:17], off
	v_lshl_add_u64 v[16:17], s[26:27], 0, v[178:179]
	s_mov_b32 m0, s69
	s_nop 0
	global_load_lds_dwordx4 v[16:17], off
	v_lshl_add_u64 v[16:17], v[22:23], 0, s[44:45]
	s_mov_b32 m0, s52
	s_nop 0
	global_load_lds_dwordx4 v[16:17], off
	v_lshl_add_u64 v[16:17], v[20:21], 0, s[44:45]
	s_mov_b32 m0, s53
	s_nop 0
	global_load_lds_dwordx4 v[16:17], off
	s_waitcnt vmcnt(8) lgkmcnt(0)
	s_barrier
	s_setprio 1
	v_mfma_scale_f32_16x16x128_f8f6f4 v[100:103], v[24:31], v[214:221], v[100:103], v232, v232 op_sel_hi:[0,0,0]
	v_mfma_scale_f32_16x16x128_f8f6f4 v[96:99], v[188:195], v[214:221], v[96:99], v232, v232 op_sel_hi:[0,0,0]
	v_mfma_scale_f32_16x16x128_f8f6f4 v[84:87], v[24:31], v[222:229], v[84:87], v232, v232 op_sel_hi:[0,0,0]
	v_mfma_scale_f32_16x16x128_f8f6f4 v[80:83], v[188:195], v[222:229], v[80:83], v232, v232 op_sel_hi:[0,0,0]
	v_mfma_scale_f32_16x16x128_f8f6f4 v[68:71], v[24:31], v[238:245], v[68:71], v232, v232 op_sel_hi:[0,0,0]
	v_mfma_scale_f32_16x16x128_f8f6f4 v[64:67], v[188:195], v[238:245], v[64:67], v232, v232 op_sel_hi:[0,0,0]
	v_mfma_scale_f32_16x16x128_f8f6f4 v[52:55], v[24:31], v[246:253], v[52:55], v232, v232 op_sel_hi:[0,0,0]
	v_mfma_scale_f32_16x16x128_f8f6f4 v[48:51], v[188:195], v[246:253], v[48:51], v232, v232 op_sel_hi:[0,0,0]
	s_setprio 0
	s_setprio 1
	v_mfma_scale_f32_16x16x128_f8f6f4 v[108:111], v[8:15], v[214:221], v[108:111], v232, v232 op_sel_hi:[0,0,0]
	v_mfma_scale_f32_16x16x128_f8f6f4 v[104:107], v[0:7], v[214:221], v[104:107], v232, v232 op_sel_hi:[0,0,0]
	v_mfma_scale_f32_16x16x128_f8f6f4 v[92:95], v[8:15], v[222:229], v[92:95], v232, v232 op_sel_hi:[0,0,0]
	v_mfma_scale_f32_16x16x128_f8f6f4 v[88:91], v[0:7], v[222:229], v[88:91], v232, v232 op_sel_hi:[0,0,0]
	v_mfma_scale_f32_16x16x128_f8f6f4 v[76:79], v[8:15], v[238:245], v[76:79], v232, v232 op_sel_hi:[0,0,0]
	v_mfma_scale_f32_16x16x128_f8f6f4 v[72:75], v[0:7], v[238:245], v[72:75], v232, v232 op_sel_hi:[0,0,0]
	v_mfma_scale_f32_16x16x128_f8f6f4 v[60:63], v[8:15], v[246:253], v[60:63], v232, v232 op_sel_hi:[0,0,0]
	v_mfma_scale_f32_16x16x128_f8f6f4 v[56:59], v[0:7], v[246:253], v[56:59], v232, v232 op_sel_hi:[0,0,0]
	s_setprio 0
	s_barrier
	s_add_i32 s82, s82, 2
	s_add_u32 s22, s22, 0x100
	s_addc_u32 s23, s23, 0
	s_cmp_gt_u32 s82, 5
	s_cbranch_scc1 .LBB0_964

.LBB0_1003:
	s_andn2_saveexec_b64 s[8:9], s[22:23]
	s_cbranch_execz .LBB0_890
	s_mov_b64 s[8:9], exec
	buffer_wbl2 sc1
	s_waitcnt vmcnt(0) lgkmcnt(0)
	v_mbcnt_lo_u32_b32 v1, s8, 0
	v_mbcnt_hi_u32_b32 v1, s9, v1
	v_cmp_eq_u32_e32 vcc, 0, v1
	s_and_saveexec_b64 s[14:15], vcc
	s_cbranch_execz .LBB0_1006
	s_bcnt1_i32_b64 s8, s[8:9]
	v_mov_b32_e32 v2, s8
	v_mov_b32_e32 v3, 0x7000
	global_atomic_add v2, v3, v2, s[4:5] offset:1024 sc0

.LBB0_1055:
	s_ashr_i32 s37, s36, 31
	s_lshl_b64 s[22:23], s[36:37], 18
	s_add_u32 s22, s81, s22
	s_addc_u32 s23, s83, s23
	s_and_b64 s[56:57], s[24:25], exec
	s_cselect_b32 s37, s23, s95
	s_cselect_b32 s56, s22, s94
	s_ashr_i32 s27, s26, 31
	s_lshl_b64 s[26:27], s[26:27], 12
	s_add_u32 s29, s41, s26
	s_addc_u32 s35, s48, s27
	s_lshl_b32 s96, s28, 8
	s_ashr_i32 s97, s96, 31
	s_lshl_b64 s[26:27], s[96:97], 2
	s_add_u32 s26, s29, s26
	s_addc_u32 s27, s35, s27
	s_lshl_b32 s28, s69, 2
	s_add_u32 s26, s26, s28
	s_addc_u32 s27, s27, 0
	v_mov_b32_e32 v183, v213
	v_add_lshl_u32 v0, v231, s54, 10
	v_add_u32_e32 v1, 0x20000, v234
	s_add_i32 s61, 0, 0x14000
	s_add_i32 s59, 0, 0x10000
	v_lshl_add_u64 v[184:185], s[26:27], 0, v[182:183]
	v_add_u32_e32 v183, v0, v234
	v_add_u32_e32 v205, v1, v0
	v_add_lshl_u32 v0, v194, s54, 10
	v_add_u32_e32 v1, 0x20000, v235
	v_add_u32_e32 v208, s61, v199
	v_add_u32_e32 v209, s59, v199
	v_add_u32_e32 v206, v0, v235
	v_add_u32_e32 v207, v1, v0
	ds_read_b128 v[0:3], v208
	ds_read_b128 v[4:7], v208 offset:1024
	ds_read_b128 v[8:11], v208 offset:2048
	ds_read_b128 v[12:15], v208 offset:3072
	ds_read_b128 v[20:23], v209 offset:3072
	ds_read_b128 v[16:19], v209 offset:2048
	ds_read_b128 v[28:31], v209 offset:1024
	ds_read_b128 v[24:27], v209
	s_add_i32 s57, s14, 0xc000
	s_mov_b32 m0, s57
	s_add_i32 s58, s14, 0xe000
	ds_read_b128 v[48:51], v204
	ds_read_b128 v[52:55], v204 offset:1024
	ds_read_b128 v[56:59], v204 offset:2048
	ds_read_b128 v[60:63], v204 offset:3072
	ds_read_b128 v[64:67], v204 offset:4096
	ds_read_b128 v[68:71], v204 offset:5120
	ds_read_b128 v[72:75], v204 offset:6144
	ds_read_b128 v[76:79], v204 offset:7168
	global_load_lds_dwordx4 v196, s[30:31]
	s_mov_b32 m0, s58
	s_nop 0
	global_load_lds_dwordx4 v197, s[30:31]
	s_waitcnt vmcnt(8) lgkmcnt(0)
	s_barrier
	s_setprio 1
	v_mfma_scale_f32_16x16x128_f8f6f4 v[172:175], v[24:31], v[48:55], 0, v232, v232 op_sel_hi:[0,0,0]
	v_mfma_scale_f32_16x16x128_f8f6f4 v[168:171], v[16:23], v[48:55], 0, v232, v232 op_sel_hi:[0,0,0]
	v_mfma_scale_f32_16x16x128_f8f6f4 v[164:167], v[24:31], v[56:63], 0, v232, v232 op_sel_hi:[0,0,0]
	v_mfma_scale_f32_16x16x128_f8f6f4 v[160:163], v[16:23], v[56:63], 0, v232, v232 op_sel_hi:[0,0,0]
	v_mfma_scale_f32_16x16x128_f8f6f4 v[156:159], v[24:31], v[64:71], 0, v232, v232 op_sel_hi:[0,0,0]
	v_mfma_scale_f32_16x16x128_f8f6f4 v[152:155], v[16:23], v[64:71], 0, v232, v232 op_sel_hi:[0,0,0]
	v_mfma_scale_f32_16x16x128_f8f6f4 v[148:151], v[24:31], v[72:79], 0, v232, v232 op_sel_hi:[0,0,0]
	v_mfma_scale_f32_16x16x128_f8f6f4 v[144:147], v[16:23], v[72:79], 0, v232, v232 op_sel_hi:[0,0,0]
	s_setprio 0
	s_setprio 1
	v_mfma_scale_f32_16x16x128_f8f6f4 v[140:143], v[0:7], v[48:55], 0, v232, v232 op_sel_hi:[0,0,0]
	v_mfma_scale_f32_16x16x128_f8f6f4 v[136:139], v[8:15], v[48:55], 0, v232, v232 op_sel_hi:[0,0,0]
	v_mfma_scale_f32_16x16x128_f8f6f4 v[132:135], v[0:7], v[56:63], 0, v232, v232 op_sel_hi:[0,0,0]
	v_mfma_scale_f32_16x16x128_f8f6f4 v[128:131], v[8:15], v[56:63], 0, v232, v232 op_sel_hi:[0,0,0]
	v_mfma_scale_f32_16x16x128_f8f6f4 v[116:119], v[0:7], v[64:71], 0, v232, v232 op_sel_hi:[0,0,0]
	v_mfma_scale_f32_16x16x128_f8f6f4 v[112:115], v[8:15], v[64:71], 0, v232, v232 op_sel_hi:[0,0,0]
	v_mfma_scale_f32_16x16x128_f8f6f4 v[100:103], v[0:7], v[72:79], 0, v232, v232 op_sel_hi:[0,0,0]
	v_mfma_scale_f32_16x16x128_f8f6f4 v[96:99], v[8:15], v[72:79], 0, v232, v232 op_sel_hi:[0,0,0]
	s_setprio 0
	s_barrier
	s_add_i32 s59, s59, s68
	v_lshl_add_u64 v[186:187], s[94:95], 0, v[176:177]
	s_add_i32 s60, s59, 0x2000
	v_lshl_add_u64 v[64:65], v[186:187], 0, s[46:47]
	s_mov_b32 m0, s59
	v_lshl_add_u64 v[188:189], s[94:95], 0, v[178:179]
	s_add_u32 s26, s94, 0x20100
	ds_read_b128 v[48:51], v204 offset:16384
	ds_read_b128 v[52:55], v204 offset:17408
	ds_read_b128 v[56:59], v204 offset:18432
	ds_read_b128 v[60:63], v204 offset:19456
	ds_read_b128 v[214:217], v204 offset:20480
	ds_read_b128 v[218:221], v204 offset:21504
	ds_read_b128 v[222:225], v204 offset:22528
	ds_read_b128 v[226:229], v204 offset:23552
	global_load_lds_dwordx4 v[64:65], off
	v_lshl_add_u64 v[64:65], v[188:189], 0, s[46:47]
	s_mov_b32 m0, s60
	s_addc_u32 s27, s95, 0
	s_add_i32 s61, s61, s68
	global_load_lds_dwordx4 v[64:65], off
	v_lshl_add_u64 v[64:65], s[26:27], 0, v[176:177]
	s_mov_b32 m0, s61
	s_add_i32 s62, s61, 0x2000
	global_load_lds_dwordx4 v[64:65], off
	v_lshl_add_u64 v[64:65], s[26:27], 0, v[178:179]
	s_mov_b32 m0, s62
	s_nop 0
	global_load_lds_dwordx4 v[64:65], off
	s_mov_b32 m0, s14
	s_nop 0
	global_load_lds_dwordx4 v212, s[88:89]
	s_mov_b32 m0, s15
	s_nop 0
	global_load_lds_dwordx4 v180, s[88:89]
	s_waitcnt vmcnt(8) lgkmcnt(0)
	s_barrier
	s_setprio 1
	v_mfma_scale_f32_16x16x128_f8f6f4 v[124:127], v[24:31], v[48:55], 0, v232, v232 op_sel_hi:[0,0,0]
	v_mfma_scale_f32_16x16x128_f8f6f4 v[120:123], v[16:23], v[48:55], 0, v232, v232 op_sel_hi:[0,0,0]
	v_mfma_scale_f32_16x16x128_f8f6f4 v[108:111], v[24:31], v[56:63], 0, v232, v232 op_sel_hi:[0,0,0]
	v_mfma_scale_f32_16x16x128_f8f6f4 v[104:107], v[16:23], v[56:63], 0, v232, v232 op_sel_hi:[0,0,0]
	v_mfma_scale_f32_16x16x128_f8f6f4 v[92:95], v[24:31], v[214:221], 0, v232, v232 op_sel_hi:[0,0,0]
	v_mfma_scale_f32_16x16x128_f8f6f4 v[88:91], v[16:23], v[214:221], 0, v232, v232 op_sel_hi:[0,0,0]
	v_mfma_scale_f32_16x16x128_f8f6f4 v[84:87], v[24:31], v[222:229], 0, v232, v232 op_sel_hi:[0,0,0]
	v_mfma_scale_f32_16x16x128_f8f6f4 v[80:83], v[16:23], v[222:229], 0, v232, v232 op_sel_hi:[0,0,0]
	s_setprio 0
	s_setprio 1
	v_mfma_scale_f32_16x16x128_f8f6f4 v[76:79], v[0:7], v[48:55], 0, v232, v232 op_sel_hi:[0,0,0]
	v_mfma_scale_f32_16x16x128_f8f6f4 v[72:75], v[8:15], v[48:55], 0, v232, v232 op_sel_hi:[0,0,0]
	v_mfma_scale_f32_16x16x128_f8f6f4 v[68:71], v[0:7], v[56:63], 0, v232, v232 op_sel_hi:[0,0,0]
	v_mfma_scale_f32_16x16x128_f8f6f4 v[64:67], v[8:15], v[56:63], 0, v232, v232 op_sel_hi:[0,0,0]
	v_mfma_scale_f32_16x16x128_f8f6f4 v[60:63], v[0:7], v[214:221], 0, v232, v232 op_sel_hi:[0,0,0]
	v_mfma_scale_f32_16x16x128_f8f6f4 v[56:59], v[8:15], v[214:221], 0, v232, v232 op_sel_hi:[0,0,0]
	v_mfma_scale_f32_16x16x128_f8f6f4 v[52:55], v[0:7], v[222:229], 0, v232, v232 op_sel_hi:[0,0,0]
	v_mfma_scale_f32_16x16x128_f8f6f4 v[48:51], v[8:15], v[222:229], 0, v232, v232 op_sel_hi:[0,0,0]
	s_setprio 0
	s_barrier
	s_add_i32 s63, 0, 0x18000
	s_add_i32 s65, 0, 0x1c000
	v_add_u32_e32 v210, s63, v199
	v_add_u32_e32 v211, s65, v199
	ds_read_b128 v[24:27], v210
	ds_read_b128 v[28:31], v210 offset:1024
	ds_read_b128 v[16:19], v210 offset:2048
	ds_read_b128 v[20:23], v210 offset:3072
	ds_read_b128 v[8:11], v211
	ds_read_b128 v[12:15], v211 offset:1024
	ds_read_b128 v[0:3], v211 offset:2048
	ds_read_b128 v[4:7], v211 offset:3072
	s_mov_b32 m0, s38
	ds_read_b128 v[214:217], v204 offset:32768
	ds_read_b128 v[218:221], v204 offset:33792
	ds_read_b128 v[222:225], v204 offset:34816
	ds_read_b128 v[226:229], v204 offset:35840
	ds_read_b128 v[238:241], v204 offset:36864
	ds_read_b128 v[242:245], v204 offset:37888
	ds_read_b128 v[246:249], v204 offset:38912
	ds_read_b128 v[250:253], v204 offset:39936
	global_load_lds_dwordx4 v196, s[88:89]
	s_mov_b32 m0, s40
	s_nop 0
	global_load_lds_dwordx4 v197, s[88:89]
	s_waitcnt vmcnt(8) lgkmcnt(0)
	s_barrier
	s_setprio 1
	v_mfma_scale_f32_16x16x128_f8f6f4 v[172:175], v[24:31], v[214:221], v[172:175], v232, v232 op_sel_hi:[0,0,0]
	v_mfma_scale_f32_16x16x128_f8f6f4 v[168:171], v[16:23], v[214:221], v[168:171], v232, v232 op_sel_hi:[0,0,0]
	v_mfma_scale_f32_16x16x128_f8f6f4 v[164:167], v[24:31], v[222:229], v[164:167], v232, v232 op_sel_hi:[0,0,0]
	v_mfma_scale_f32_16x16x128_f8f6f4 v[160:163], v[16:23], v[222:229], v[160:163], v232, v232 op_sel_hi:[0,0,0]
	v_mfma_scale_f32_16x16x128_f8f6f4 v[156:159], v[24:31], v[238:245], v[156:159], v232, v232 op_sel_hi:[0,0,0]
	v_mfma_scale_f32_16x16x128_f8f6f4 v[152:155], v[16:23], v[238:245], v[152:155], v232, v232 op_sel_hi:[0,0,0]
	v_mfma_scale_f32_16x16x128_f8f6f4 v[148:151], v[24:31], v[246:253], v[148:151], v232, v232 op_sel_hi:[0,0,0]
	v_mfma_scale_f32_16x16x128_f8f6f4 v[144:147], v[16:23], v[246:253], v[144:147], v232, v232 op_sel_hi:[0,0,0]
	s_setprio 0
	s_setprio 1
	v_mfma_scale_f32_16x16x128_f8f6f4 v[140:143], v[8:15], v[214:221], v[140:143], v232, v232 op_sel_hi:[0,0,0]
	v_mfma_scale_f32_16x16x128_f8f6f4 v[136:139], v[0:7], v[214:221], v[136:139], v232, v232 op_sel_hi:[0,0,0]
	v_mfma_scale_f32_16x16x128_f8f6f4 v[132:135], v[8:15], v[222:229], v[132:135], v232, v232 op_sel_hi:[0,0,0]
	v_mfma_scale_f32_16x16x128_f8f6f4 v[128:131], v[0:7], v[222:229], v[128:131], v232, v232 op_sel_hi:[0,0,0]
	v_mfma_scale_f32_16x16x128_f8f6f4 v[116:119], v[8:15], v[238:245], v[116:119], v232, v232 op_sel_hi:[0,0,0]
	v_mfma_scale_f32_16x16x128_f8f6f4 v[112:115], v[0:7], v[238:245], v[112:115], v232, v232 op_sel_hi:[0,0,0]
	v_mfma_scale_f32_16x16x128_f8f6f4 v[100:103], v[8:15], v[246:253], v[100:103], v232, v232 op_sel_hi:[0,0,0]
	v_mfma_scale_f32_16x16x128_f8f6f4 v[96:99], v[0:7], v[246:253], v[96:99], v232, v232 op_sel_hi:[0,0,0]
	s_setprio 0
	s_barrier
	s_add_i32 s63, s63, s68
	s_add_i32 s64, s63, 0x2000
	v_lshl_add_u64 v[186:187], v[186:187], 0, s[84:85]
	s_mov_b32 m0, s63
	s_add_u32 s26, s94, 0x20180
	ds_read_b128 v[214:217], v204 offset:49152
	ds_read_b128 v[218:221], v204 offset:50176
	ds_read_b128 v[222:225], v204 offset:51200
	ds_read_b128 v[226:229], v204 offset:52224
	ds_read_b128 v[238:241], v204 offset:53248
	ds_read_b128 v[242:245], v204 offset:54272
	ds_read_b128 v[246:249], v204 offset:55296
	ds_read_b128 v[250:253], v204 offset:56320
	global_load_lds_dwordx4 v[186:187], off
	v_lshl_add_u64 v[186:187], v[188:189], 0, s[84:85]
	s_mov_b32 m0, s64
	s_addc_u32 s27, s95, 0
	s_add_i32 s65, s65, s68
	global_load_lds_dwordx4 v[186:187], off
	v_lshl_add_u64 v[186:187], s[26:27], 0, v[176:177]
	s_mov_b32 m0, s65
	s_add_i32 s71, s65, 0x2000
	global_load_lds_dwordx4 v[186:187], off
	v_lshl_add_u64 v[186:187], s[26:27], 0, v[178:179]
	s_mov_b32 m0, s71
	s_nop 0
	global_load_lds_dwordx4 v[186:187], off
	s_mov_b32 m0, s49
	s_nop 0
	global_load_lds_dwordx4 v212, s[90:91]
	s_mov_b32 m0, s50
	s_nop 0
	global_load_lds_dwordx4 v180, s[90:91]
	s_waitcnt vmcnt(8) lgkmcnt(0)
	s_barrier
	s_setprio 1
	v_mfma_scale_f32_16x16x128_f8f6f4 v[124:127], v[24:31], v[214:221], v[124:127], v232, v232 op_sel_hi:[0,0,0]
	v_mfma_scale_f32_16x16x128_f8f6f4 v[120:123], v[16:23], v[214:221], v[120:123], v232, v232 op_sel_hi:[0,0,0]
	v_mfma_scale_f32_16x16x128_f8f6f4 v[108:111], v[24:31], v[222:229], v[108:111], v232, v232 op_sel_hi:[0,0,0]
	v_mfma_scale_f32_16x16x128_f8f6f4 v[104:107], v[16:23], v[222:229], v[104:107], v232, v232 op_sel_hi:[0,0,0]
	v_mfma_scale_f32_16x16x128_f8f6f4 v[92:95], v[24:31], v[238:245], v[92:95], v232, v232 op_sel_hi:[0,0,0]
	v_mfma_scale_f32_16x16x128_f8f6f4 v[88:91], v[16:23], v[238:245], v[88:91], v232, v232 op_sel_hi:[0,0,0]
	v_mfma_scale_f32_16x16x128_f8f6f4 v[84:87], v[24:31], v[246:253], v[84:87], v232, v232 op_sel_hi:[0,0,0]
	v_mfma_scale_f32_16x16x128_f8f6f4 v[80:83], v[16:23], v[246:253], v[80:83], v232, v232 op_sel_hi:[0,0,0]
	s_setprio 0
	s_setprio 1
	v_mfma_scale_f32_16x16x128_f8f6f4 v[76:79], v[8:15], v[214:221], v[76:79], v232, v232 op_sel_hi:[0,0,0]
	v_mfma_scale_f32_16x16x128_f8f6f4 v[72:75], v[0:7], v[214:221], v[72:75], v232, v232 op_sel_hi:[0,0,0]
	v_mfma_scale_f32_16x16x128_f8f6f4 v[68:71], v[8:15], v[222:229], v[68:71], v232, v232 op_sel_hi:[0,0,0]
	v_mfma_scale_f32_16x16x128_f8f6f4 v[64:67], v[0:7], v[222:229], v[64:67], v232, v232 op_sel_hi:[0,0,0]
	v_mfma_scale_f32_16x16x128_f8f6f4 v[60:63], v[8:15], v[238:245], v[60:63], v232, v232 op_sel_hi:[0,0,0]
	v_mfma_scale_f32_16x16x128_f8f6f4 v[56:59], v[0:7], v[238:245], v[56:59], v232, v232 op_sel_hi:[0,0,0]
	v_mfma_scale_f32_16x16x128_f8f6f4 v[52:55], v[8:15], v[246:253], v[52:55], v232, v232 op_sel_hi:[0,0,0]
	v_mfma_scale_f32_16x16x128_f8f6f4 v[48:51], v[0:7], v[246:253], v[48:51], v232, v232 op_sel_hi:[0,0,0]
	s_setprio 0
	s_barrier
	s_add_u32 s82, s94, 0x200
	s_addc_u32 s97, s95, 0
	s_mov_b32 s35, 0
	s_mov_b64 s[94:95], 0
	s_branch .LBB0_1057
.LBB0_1056:
	ds_read_b128 v[24:27], v209
	ds_read_b128 v[28:31], v209 offset:1024
	ds_read_b128 v[214:217], v209 offset:2048
	ds_read_b128 v[218:221], v209 offset:3072
	ds_read_b128 v[8:11], v208
	ds_read_b128 v[12:15], v208 offset:1024
	ds_read_b128 v[0:3], v208 offset:2048
	ds_read_b128 v[4:7], v208 offset:3072
	s_add_u32 vcc_lo, s94, 0x200
	s_addc_u32 vcc_hi, s95, 0
	s_and_b64 s[28:29], s[26:27], exec
	s_cselect_b32 vcc_hi, 0, vcc_hi
	s_cselect_b32 vcc_lo, 0, vcc_lo
	s_add_u32 s28, s82, s94
	s_addc_u32 s29, s97, s95
	s_and_b64 s[26:27], s[26:27], exec
	s_cselect_b32 s27, s37, s29
	s_cselect_b32 s26, s56, s28
	s_add_u32 s28, s90, s94
	s_addc_u32 s29, s91, s95
	s_mov_b32 m0, s57
	ds_read_b128 v[222:225], v204
	ds_read_b128 v[226:229], v204 offset:1024
	ds_read_b128 v[238:241], v204 offset:2048
	ds_read_b128 v[242:245], v204 offset:3072
	ds_read_b128 v[246:249], v204 offset:4096
	ds_read_b128 v[250:253], v204 offset:5120
	ds_read_b128 v[186:189], v204 offset:6144
	ds_read_b128 v[190:193], v204 offset:7168
	global_load_lds_dwordx4 v17, s[28:29]
	s_mov_b32 m0, s58
	s_nop 0
	global_load_lds_dwordx4 v16, s[28:29]
	s_waitcnt vmcnt(8) lgkmcnt(0)
	s_barrier
	s_setprio 1
	v_mfma_scale_f32_16x16x128_f8f6f4 v[172:175], v[24:31], v[222:229], v[172:175], v232, v232 op_sel_hi:[0,0,0]
	v_mfma_scale_f32_16x16x128_f8f6f4 v[168:171], v[214:221], v[222:229], v[168:171], v232, v232 op_sel_hi:[0,0,0]
	v_mfma_scale_f32_16x16x128_f8f6f4 v[164:167], v[24:31], v[238:245], v[164:167], v232, v232 op_sel_hi:[0,0,0]
	v_mfma_scale_f32_16x16x128_f8f6f4 v[160:163], v[214:221], v[238:245], v[160:163], v232, v232 op_sel_hi:[0,0,0]
	v_mfma_scale_f32_16x16x128_f8f6f4 v[156:159], v[24:31], v[246:253], v[156:159], v232, v232 op_sel_hi:[0,0,0]
	v_mfma_scale_f32_16x16x128_f8f6f4 v[152:155], v[214:221], v[246:253], v[152:155], v232, v232 op_sel_hi:[0,0,0]
	v_mfma_scale_f32_16x16x128_f8f6f4 v[148:151], v[24:31], v[186:193], v[148:151], v232, v232 op_sel_hi:[0,0,0]
	v_mfma_scale_f32_16x16x128_f8f6f4 v[144:147], v[214:221], v[186:193], v[144:147], v232, v232 op_sel_hi:[0,0,0]
	s_setprio 0
	s_setprio 1
	v_mfma_scale_f32_16x16x128_f8f6f4 v[140:143], v[8:15], v[222:229], v[140:143], v232, v232 op_sel_hi:[0,0,0]
	v_mfma_scale_f32_16x16x128_f8f6f4 v[136:139], v[0:7], v[222:229], v[136:139], v232, v232 op_sel_hi:[0,0,0]
	v_mfma_scale_f32_16x16x128_f8f6f4 v[132:135], v[8:15], v[238:245], v[132:135], v232, v232 op_sel_hi:[0,0,0]
	v_mfma_scale_f32_16x16x128_f8f6f4 v[128:131], v[0:7], v[238:245], v[128:131], v232, v232 op_sel_hi:[0,0,0]
	v_mfma_scale_f32_16x16x128_f8f6f4 v[116:119], v[8:15], v[246:253], v[116:119], v232, v232 op_sel_hi:[0,0,0]
	v_mfma_scale_f32_16x16x128_f8f6f4 v[112:115], v[0:7], v[246:253], v[112:115], v232, v232 op_sel_hi:[0,0,0]
	v_mfma_scale_f32_16x16x128_f8f6f4 v[100:103], v[8:15], v[186:193], v[100:103], v232, v232 op_sel_hi:[0,0,0]
	v_mfma_scale_f32_16x16x128_f8f6f4 v[96:99], v[0:7], v[186:193], v[96:99], v232, v232 op_sel_hi:[0,0,0]
	s_setprio 0
	s_barrier
	s_mov_b32 m0, s59
	v_lshl_add_u64 v[16:17], s[26:27], 0, v[176:177]
	s_add_u32 s28, s26, 0x20000
	ds_read_b128 v[186:189], v204 offset:16384
	ds_read_b128 v[190:193], v204 offset:17408
	ds_read_b128 v[222:225], v204 offset:18432
	ds_read_b128 v[226:229], v204 offset:19456
	ds_read_b128 v[238:241], v204 offset:20480
	ds_read_b128 v[242:245], v204 offset:21504
	ds_read_b128 v[246:249], v204 offset:22528
	ds_read_b128 v[250:253], v204 offset:23552
	global_load_lds_dwordx4 v[16:17], off
	v_lshl_add_u64 v[18:19], s[26:27], 0, v[178:179]
	s_mov_b32 m0, s60
	s_addc_u32 s29, s27, 0
	global_load_lds_dwordx4 v[18:19], off
	v_lshl_add_u64 v[20:21], s[28:29], 0, v[176:177]
	s_mov_b32 m0, s61
	v_mov_b32_e32 v181, v213
	global_load_lds_dwordx4 v[20:21], off
	v_lshl_add_u64 v[20:21], s[28:29], 0, v[178:179]
	s_mov_b32 m0, s62
	s_add_u32 s28, s10, vcc_lo
	global_load_lds_dwordx4 v[20:21], off
	s_addc_u32 s29, s11, vcc_hi
	s_mov_b32 m0, s14
	v_lshl_add_u64 v[22:23], s[28:29], 0, v[212:213]
	global_load_lds_dwordx4 v212, s[28:29]
	s_mov_b32 m0, s15
	v_lshl_add_u64 v[20:21], s[28:29], 0, v[180:181]
	global_load_lds_dwordx4 v180, s[28:29]
	s_waitcnt vmcnt(8) lgkmcnt(0)
	s_barrier
	s_setprio 1
	v_mfma_scale_f32_16x16x128_f8f6f4 v[124:127], v[24:31], v[186:193], v[124:127], v232, v232 op_sel_hi:[0,0,0]
	v_mfma_scale_f32_16x16x128_f8f6f4 v[120:123], v[214:221], v[186:193], v[120:123], v232, v232 op_sel_hi:[0,0,0]
	v_mfma_scale_f32_16x16x128_f8f6f4 v[108:111], v[24:31], v[222:229], v[108:111], v232, v232 op_sel_hi:[0,0,0]
	v_mfma_scale_f32_16x16x128_f8f6f4 v[104:107], v[214:221], v[222:229], v[104:107], v232, v232 op_sel_hi:[0,0,0]
	v_mfma_scale_f32_16x16x128_f8f6f4 v[92:95], v[24:31], v[238:245], v[92:95], v232, v232 op_sel_hi:[0,0,0]
	v_mfma_scale_f32_16x16x128_f8f6f4 v[88:91], v[214:221], v[238:245], v[88:91], v232, v232 op_sel_hi:[0,0,0]
	v_mfma_scale_f32_16x16x128_f8f6f4 v[84:87], v[24:31], v[246:253], v[84:87], v232, v232 op_sel_hi:[0,0,0]
	v_mfma_scale_f32_16x16x128_f8f6f4 v[80:83], v[214:221], v[246:253], v[80:83], v232, v232 op_sel_hi:[0,0,0]
	s_setprio 0
	s_setprio 1
	v_mfma_scale_f32_16x16x128_f8f6f4 v[76:79], v[8:15], v[186:193], v[76:79], v232, v232 op_sel_hi:[0,0,0]
	v_mfma_scale_f32_16x16x128_f8f6f4 v[72:75], v[0:7], v[186:193], v[72:75], v232, v232 op_sel_hi:[0,0,0]
	v_mfma_scale_f32_16x16x128_f8f6f4 v[68:71], v[8:15], v[222:229], v[68:71], v232, v232 op_sel_hi:[0,0,0]
	v_mfma_scale_f32_16x16x128_f8f6f4 v[64:67], v[0:7], v[222:229], v[64:67], v232, v232 op_sel_hi:[0,0,0]
	v_mfma_scale_f32_16x16x128_f8f6f4 v[60:63], v[8:15], v[238:245], v[60:63], v232, v232 op_sel_hi:[0,0,0]
	v_mfma_scale_f32_16x16x128_f8f6f4 v[56:59], v[0:7], v[238:245], v[56:59], v232, v232 op_sel_hi:[0,0,0]
	v_mfma_scale_f32_16x16x128_f8f6f4 v[52:55], v[8:15], v[246:253], v[52:55], v232, v232 op_sel_hi:[0,0,0]
	v_mfma_scale_f32_16x16x128_f8f6f4 v[48:51], v[0:7], v[246:253], v[48:51], v232, v232 op_sel_hi:[0,0,0]
	s_setprio 0
	s_barrier
	ds_read_b128 v[24:27], v210
	ds_read_b128 v[28:31], v210 offset:1024
	ds_read_b128 v[186:189], v210 offset:2048
	ds_read_b128 v[190:193], v210 offset:3072
	ds_read_b128 v[8:11], v211
	ds_read_b128 v[12:15], v211 offset:1024
	ds_read_b128 v[0:3], v211 offset:2048
	ds_read_b128 v[4:7], v211 offset:3072
	s_mov_b32 m0, s38
	ds_read_b128 v[214:217], v204 offset:32768
	ds_read_b128 v[218:221], v204 offset:33792
	ds_read_b128 v[222:225], v204 offset:34816
	ds_read_b128 v[226:229], v204 offset:35840
	ds_read_b128 v[238:241], v204 offset:36864
	ds_read_b128 v[242:245], v204 offset:37888
	ds_read_b128 v[246:249], v204 offset:38912
	ds_read_b128 v[250:253], v204 offset:39936
	global_load_lds_dwordx4 v196, s[28:29]
	s_mov_b32 m0, s40
	s_nop 0
	global_load_lds_dwordx4 v197, s[28:29]
	s_waitcnt vmcnt(8) lgkmcnt(0)
	s_barrier
	s_setprio 1
	v_mfma_scale_f32_16x16x128_f8f6f4 v[172:175], v[24:31], v[214:221], v[172:175], v232, v232 op_sel_hi:[0,0,0]
	v_mfma_scale_f32_16x16x128_f8f6f4 v[168:171], v[186:193], v[214:221], v[168:171], v232, v232 op_sel_hi:[0,0,0]
	v_mfma_scale_f32_16x16x128_f8f6f4 v[164:167], v[24:31], v[222:229], v[164:167], v232, v232 op_sel_hi:[0,0,0]
	v_mfma_scale_f32_16x16x128_f8f6f4 v[160:163], v[186:193], v[222:229], v[160:163], v232, v232 op_sel_hi:[0,0,0]
	v_mfma_scale_f32_16x16x128_f8f6f4 v[156:159], v[24:31], v[238:245], v[156:159], v232, v232 op_sel_hi:[0,0,0]
	v_mfma_scale_f32_16x16x128_f8f6f4 v[152:155], v[186:193], v[238:245], v[152:155], v232, v232 op_sel_hi:[0,0,0]
	v_mfma_scale_f32_16x16x128_f8f6f4 v[148:151], v[24:31], v[246:253], v[148:151], v232, v232 op_sel_hi:[0,0,0]
	v_mfma_scale_f32_16x16x128_f8f6f4 v[144:147], v[186:193], v[246:253], v[144:147], v232, v232 op_sel_hi:[0,0,0]
	s_setprio 0
	s_setprio 1
	v_mfma_scale_f32_16x16x128_f8f6f4 v[140:143], v[8:15], v[214:221], v[140:143], v232, v232 op_sel_hi:[0,0,0]
	v_mfma_scale_f32_16x16x128_f8f6f4 v[136:139], v[0:7], v[214:221], v[136:139], v232, v232 op_sel_hi:[0,0,0]
	v_mfma_scale_f32_16x16x128_f8f6f4 v[132:135], v[8:15], v[222:229], v[132:135], v232, v232 op_sel_hi:[0,0,0]
	v_mfma_scale_f32_16x16x128_f8f6f4 v[128:131], v[0:7], v[222:229], v[128:131], v232, v232 op_sel_hi:[0,0,0]
	v_mfma_scale_f32_16x16x128_f8f6f4 v[116:119], v[8:15], v[238:245], v[116:119], v232, v232 op_sel_hi:[0,0,0]
	v_mfma_scale_f32_16x16x128_f8f6f4 v[112:115], v[0:7], v[238:245], v[112:115], v232, v232 op_sel_hi:[0,0,0]
	v_mfma_scale_f32_16x16x128_f8f6f4 v[100:103], v[8:15], v[246:253], v[100:103], v232, v232 op_sel_hi:[0,0,0]
	v_mfma_scale_f32_16x16x128_f8f6f4 v[96:99], v[0:7], v[246:253], v[96:99], v232, v232 op_sel_hi:[0,0,0]
	s_setprio 0
	s_barrier
	s_mov_b32 m0, s63
	v_lshl_add_u64 v[16:17], v[16:17], 0, s[44:45]
	s_add_u32 s26, s26, 0x20080
	ds_read_b128 v[214:217], v204 offset:49152
	ds_read_b128 v[218:221], v204 offset:50176
	ds_read_b128 v[222:225], v204 offset:51200
	ds_read_b128 v[226:229], v204 offset:52224
	ds_read_b128 v[238:241], v204 offset:53248
	ds_read_b128 v[242:245], v204 offset:54272
	ds_read_b128 v[246:249], v204 offset:55296
	ds_read_b128 v[250:253], v204 offset:56320
	global_load_lds_dwordx4 v[16:17], off
	v_lshl_add_u64 v[16:17], v[18:19], 0, s[44:45]
	s_mov_b32 m0, s64
	s_addc_u32 s27, s27, 0
	global_load_lds_dwordx4 v[16:17], off
	v_lshl_add_u64 v[16:17], s[26:27], 0, v[176:177]
	s_mov_b32 m0, s65
	s_nop 0
	global_load_lds_dwordx4 v[16:17], off
	v_lshl_add_u64 v[16:17], s[26:27], 0, v[178:179]
	s_mov_b32 m0, s71
	s_nop 0
	global_load_lds_dwordx4 v[16:17], off
	v_lshl_add_u64 v[16:17], v[22:23], 0, s[44:45]
	s_mov_b32 m0, s49
	s_nop 0
	global_load_lds_dwordx4 v[16:17], off
	v_lshl_add_u64 v[16:17], v[20:21], 0, s[44:45]
	s_mov_b32 m0, s50
	s_nop 0
	global_load_lds_dwordx4 v[16:17], off
	s_waitcnt vmcnt(8) lgkmcnt(0)
	s_barrier
	s_setprio 1
	v_mfma_scale_f32_16x16x128_f8f6f4 v[124:127], v[24:31], v[214:221], v[124:127], v232, v232 op_sel_hi:[0,0,0]
	v_mfma_scale_f32_16x16x128_f8f6f4 v[120:123], v[186:193], v[214:221], v[120:123], v232, v232 op_sel_hi:[0,0,0]
	v_mfma_scale_f32_16x16x128_f8f6f4 v[108:111], v[24:31], v[222:229], v[108:111], v232, v232 op_sel_hi:[0,0,0]
	v_mfma_scale_f32_16x16x128_f8f6f4 v[104:107], v[186:193], v[222:229], v[104:107], v232, v232 op_sel_hi:[0,0,0]
	v_mfma_scale_f32_16x16x128_f8f6f4 v[92:95], v[24:31], v[238:245], v[92:95], v232, v232 op_sel_hi:[0,0,0]
	v_mfma_scale_f32_16x16x128_f8f6f4 v[88:91], v[186:193], v[238:245], v[88:91], v232, v232 op_sel_hi:[0,0,0]
	v_mfma_scale_f32_16x16x128_f8f6f4 v[84:87], v[24:31], v[246:253], v[84:87], v232, v232 op_sel_hi:[0,0,0]
	v_mfma_scale_f32_16x16x128_f8f6f4 v[80:83], v[186:193], v[246:253], v[80:83], v232, v232 op_sel_hi:[0,0,0]
	s_setprio 0
	s_setprio 1
	v_mfma_scale_f32_16x16x128_f8f6f4 v[76:79], v[8:15], v[214:221], v[76:79], v232, v232 op_sel_hi:[0,0,0]
	v_mfma_scale_f32_16x16x128_f8f6f4 v[72:75], v[0:7], v[214:221], v[72:75], v232, v232 op_sel_hi:[0,0,0]
	v_mfma_scale_f32_16x16x128_f8f6f4 v[68:71], v[8:15], v[222:229], v[68:71], v232, v232 op_sel_hi:[0,0,0]
	v_mfma_scale_f32_16x16x128_f8f6f4 v[64:67], v[0:7], v[222:229], v[64:67], v232, v232 op_sel_hi:[0,0,0]
	v_mfma_scale_f32_16x16x128_f8f6f4 v[60:63], v[8:15], v[238:245], v[60:63], v232, v232 op_sel_hi:[0,0,0]
	v_mfma_scale_f32_16x16x128_f8f6f4 v[56:59], v[0:7], v[238:245], v[56:59], v232, v232 op_sel_hi:[0,0,0]
	v_mfma_scale_f32_16x16x128_f8f6f4 v[52:55], v[8:15], v[246:253], v[52:55], v232, v232 op_sel_hi:[0,0,0]
	v_mfma_scale_f32_16x16x128_f8f6f4 v[48:51], v[0:7], v[246:253], v[48:51], v232, v232 op_sel_hi:[0,0,0]
	s_setprio 0
	s_barrier
	s_add_i32 s35, s35, 2
	s_add_u32 s94, s94, 0x100
	s_addc_u32 s95, s95, 0
	s_cmp_gt_u32 s35, 5
	s_cbranch_scc1 .LBB0_1062

.LBB0_1243:
	s_mov_b64 s[8:9], exec
	buffer_wbl2 sc1
	s_waitcnt vmcnt(0) lgkmcnt(0)
	v_mbcnt_lo_u32_b32 v1, s8, 0
	v_mbcnt_hi_u32_b32 v1, s9, v1
	v_cmp_eq_u32_e32 vcc, 0, v1
	s_and_saveexec_b64 s[10:11], vcc
	s_cbranch_execz .LBB0_1245
	s_bcnt1_i32_b64 s8, s[8:9]
	v_mov_b32_e32 v2, s8
	v_mov_b32_e32 v3, 0x7000
	global_atomic_add v2, v3, v2, s[4:5] offset:1024 sc0
